# GEMM K-loops: duplicate s_waitcnt lgkmcnt(0) after each MMA-opening barrier removed (42 sites), on top of the priority-before-barrier change
# speedup vs baseline: 1.0112x; 1.0019x over previous
.LBB0_307:
	v_add_u32_e32 v142, s63, v242
	ds_read_b128 v[130:133], v142
	ds_read_b128 v[134:137], v142 offset:1024
	ds_read_b128 v[138:141], v142 offset:2048
	ds_read_b128 v[142:145], v142 offset:3072
	s_add_i32 s19, s18, 2
	s_add_u32 s20, s14, 0x100
	s_addc_u32 s21, s15, 0
	s_cmp_eq_u32 s24, s18
	s_cselect_b32 s45, s67, s21
	s_cselect_b32 s44, s66, s20
	s_cselect_b32 s35, s71, s26
	s_cselect_b32 s34, s70, s25
	v_lshl_add_u64 v[178:179], s[14:15], 0, v[210:211]
	s_add_i32 m0, s75, 0xc000
	ds_read_b128 v[146:149], v247
	ds_read_b128 v[150:153], v247 offset:1024
	ds_read_b128 v[154:157], v247 offset:2048
	ds_read_b128 v[158:161], v247 offset:3072
	ds_read_b128 v[162:165], v247 offset:4096
	ds_read_b128 v[166:169], v247 offset:5120
	ds_read_b128 v[170:173], v247 offset:6144
	ds_read_b128 v[174:177], v247 offset:7168
	global_load_lds_dwordx4 v[178:179], off
	v_lshl_add_u64 v[178:179], s[14:15], 0, v[212:213]
	s_add_i32 m0, s75, 0xe000
	s_nop 0
	global_load_lds_dwordx4 v[178:179], off
	s_waitcnt lgkmcnt(8)
	s_setprio 1
	s_barrier
	s_waitcnt lgkmcnt(0)
	v_mfma_f32_16x16x32_bf16 v[126:129], v[130:133], v[146:149], v[126:129]
	v_mfma_f32_16x16x32_bf16 v[122:125], v[138:141], v[146:149], v[122:125]
	v_mfma_f32_16x16x32_bf16 v[118:121], v[130:133], v[154:157], v[118:121]
	v_mfma_f32_16x16x32_bf16 v[114:117], v[138:141], v[154:157], v[114:117]
	v_mfma_f32_16x16x32_bf16 v[110:113], v[130:133], v[162:165], v[110:113]
	v_mfma_f32_16x16x32_bf16 v[106:109], v[138:141], v[162:165], v[106:109]
	v_mfma_f32_16x16x32_bf16 v[102:105], v[130:133], v[170:173], v[102:105]
	v_mfma_f32_16x16x32_bf16 v[98:101], v[138:141], v[170:173], v[98:101]
	v_mfma_f32_16x16x32_bf16 v[126:129], v[134:137], v[150:153], v[126:129]
	v_mfma_f32_16x16x32_bf16 v[122:125], v[142:145], v[150:153], v[122:125]
	v_mfma_f32_16x16x32_bf16 v[118:121], v[134:137], v[158:161], v[118:121]
	v_mfma_f32_16x16x32_bf16 v[114:117], v[142:145], v[158:161], v[114:117]
	v_mfma_f32_16x16x32_bf16 v[110:113], v[134:137], v[166:169], v[110:113]
	v_mfma_f32_16x16x32_bf16 v[106:109], v[142:145], v[166:169], v[106:109]
	v_mfma_f32_16x16x32_bf16 v[102:105], v[134:137], v[174:177], v[102:105]
	v_mfma_f32_16x16x32_bf16 v[98:101], v[142:145], v[174:177], v[98:101]
	s_setprio 0
	s_barrier
	s_mov_b32 m0, s73
	v_add_u32_e32 v194, s77, v242
	v_lshl_add_u64 v[214:215], s[34:35], 0, v[0:1]
	ds_read_b128 v[178:181], v194
	ds_read_b128 v[182:185], v194 offset:1024
	ds_read_b128 v[186:189], v194 offset:2048
	ds_read_b128 v[194:197], v194 offset:3072
	global_load_lds_dwordx4 v[214:215], off
	v_lshl_add_u64 v[216:217], s[34:35], 0, v[204:205]
	s_mov_b32 m0, s74
	s_nop 0
	global_load_lds_dwordx4 v[216:217], off
	s_setprio 1
	s_barrier
	s_waitcnt lgkmcnt(0)
	v_mfma_f32_16x16x32_bf16 v[94:97], v[178:181], v[146:149], v[94:97]
	v_mfma_f32_16x16x32_bf16 v[90:93], v[186:189], v[146:149], v[90:93]
	v_mfma_f32_16x16x32_bf16 v[86:89], v[178:181], v[154:157], v[86:89]
	v_mfma_f32_16x16x32_bf16 v[82:85], v[186:189], v[154:157], v[82:85]
	v_mfma_f32_16x16x32_bf16 v[78:81], v[178:181], v[162:165], v[78:81]
	v_mfma_f32_16x16x32_bf16 v[74:77], v[186:189], v[162:165], v[74:77]
	v_mfma_f32_16x16x32_bf16 v[70:73], v[178:181], v[170:173], v[70:73]
	v_mfma_f32_16x16x32_bf16 v[66:69], v[186:189], v[170:173], v[66:69]
	v_mfma_f32_16x16x32_bf16 v[94:97], v[182:185], v[150:153], v[94:97]
	v_mfma_f32_16x16x32_bf16 v[90:93], v[194:197], v[150:153], v[90:93]
	v_mfma_f32_16x16x32_bf16 v[86:89], v[182:185], v[158:161], v[86:89]
	v_mfma_f32_16x16x32_bf16 v[82:85], v[194:197], v[158:161], v[82:85]
	v_mfma_f32_16x16x32_bf16 v[78:81], v[182:185], v[166:169], v[78:81]
	v_mfma_f32_16x16x32_bf16 v[74:77], v[194:197], v[166:169], v[74:77]
	v_mfma_f32_16x16x32_bf16 v[70:73], v[182:185], v[174:177], v[70:73]
	v_mfma_f32_16x16x32_bf16 v[66:69], v[194:197], v[174:177], v[66:69]
	s_setprio 0
	s_mov_b32 m0, s75
	v_lshl_add_u64 v[218:219], s[44:45], 0, v[0:1]
	s_barrier
	ds_read_b128 v[146:149], v247 offset:16384
	ds_read_b128 v[150:153], v247 offset:17408
	ds_read_b128 v[154:157], v247 offset:18432
	ds_read_b128 v[158:161], v247 offset:19456
	ds_read_b128 v[162:165], v247 offset:20480
	ds_read_b128 v[166:169], v247 offset:21504
	ds_read_b128 v[170:173], v247 offset:22528
	ds_read_b128 v[174:177], v247 offset:23552
	global_load_lds_dwordx4 v[218:219], off
	v_lshl_add_u64 v[220:221], s[44:45], 0, v[204:205]
	s_mov_b32 m0, s76
	s_nop 0
	global_load_lds_dwordx4 v[220:221], off
	s_setprio 1
	s_barrier
	s_waitcnt lgkmcnt(0)
	v_mfma_f32_16x16x32_bf16 v[62:65], v[130:133], v[146:149], v[62:65]
	v_mfma_f32_16x16x32_bf16 v[58:61], v[138:141], v[146:149], v[58:61]
	v_mfma_f32_16x16x32_bf16 v[54:57], v[130:133], v[154:157], v[54:57]
	v_mfma_f32_16x16x32_bf16 v[50:53], v[138:141], v[154:157], v[50:53]
	v_mfma_f32_16x16x32_bf16 v[46:49], v[130:133], v[162:165], v[46:49]
	v_mfma_f32_16x16x32_bf16 v[42:45], v[138:141], v[162:165], v[42:45]
	v_mfma_f32_16x16x32_bf16 v[38:41], v[130:133], v[170:173], v[38:41]
	v_mfma_f32_16x16x32_bf16 v[34:37], v[138:141], v[170:173], v[34:37]
	v_mfma_f32_16x16x32_bf16 v[62:65], v[134:137], v[150:153], v[62:65]
	v_mfma_f32_16x16x32_bf16 v[58:61], v[142:145], v[150:153], v[58:61]
	v_mfma_f32_16x16x32_bf16 v[54:57], v[134:137], v[158:161], v[54:57]
	v_mfma_f32_16x16x32_bf16 v[50:53], v[142:145], v[158:161], v[50:53]
	v_mfma_f32_16x16x32_bf16 v[46:49], v[134:137], v[166:169], v[46:49]
	v_mfma_f32_16x16x32_bf16 v[42:45], v[142:145], v[166:169], v[42:45]
	v_mfma_f32_16x16x32_bf16 v[38:41], v[134:137], v[174:177], v[38:41]
	v_mfma_f32_16x16x32_bf16 v[34:37], v[142:145], v[174:177], v[34:37]
	s_setprio 0
	s_barrier
	s_add_u32 s0, s34, 0xb0000
	s_addc_u32 s1, s35, 0
	s_mov_b32 m0, s78
	v_lshl_add_u64 v[130:131], s[0:1], 0, v[0:1]
	global_load_lds_dwordx4 v[130:131], off
	v_lshl_add_u64 v[130:131], s[0:1], 0, v[204:205]
	s_mov_b32 m0, s79
	s_nop 0
	global_load_lds_dwordx4 v[130:131], off
	s_waitcnt vmcnt(6)
	s_setprio 1
	s_barrier
	v_mfma_f32_16x16x32_bf16 v[30:33], v[178:181], v[146:149], v[30:33]
	v_mfma_f32_16x16x32_bf16 v[26:29], v[186:189], v[146:149], v[26:29]
	v_mfma_f32_16x16x32_bf16 v[22:25], v[178:181], v[154:157], v[22:25]
	v_mfma_f32_16x16x32_bf16 v[18:21], v[186:189], v[154:157], v[18:21]
	v_mfma_f32_16x16x32_bf16 v[14:17], v[178:181], v[162:165], v[14:17]
	v_mfma_f32_16x16x32_bf16 v[10:13], v[186:189], v[162:165], v[10:13]
	v_mfma_f32_16x16x32_bf16 v[6:9], v[178:181], v[170:173], v[6:9]
	v_mfma_f32_16x16x32_bf16 v[2:5], v[186:189], v[170:173], v[2:5]
	v_mfma_f32_16x16x32_bf16 v[30:33], v[182:185], v[150:153], v[30:33]
	v_mfma_f32_16x16x32_bf16 v[26:29], v[194:197], v[150:153], v[26:29]
	v_mfma_f32_16x16x32_bf16 v[22:25], v[182:185], v[158:161], v[22:25]
	v_mfma_f32_16x16x32_bf16 v[18:21], v[194:197], v[158:161], v[18:21]
	v_mfma_f32_16x16x32_bf16 v[14:17], v[182:185], v[166:169], v[14:17]
	v_mfma_f32_16x16x32_bf16 v[10:13], v[194:197], v[166:169], v[10:13]
	v_mfma_f32_16x16x32_bf16 v[6:9], v[182:185], v[174:177], v[6:9]
	v_mfma_f32_16x16x32_bf16 v[2:5], v[194:197], v[174:177], v[2:5]
	s_setprio 0
	v_add_u32_e32 v142, s94, v242
	s_barrier
	ds_read_b128 v[130:133], v142
	ds_read_b128 v[134:137], v142 offset:1024
	ds_read_b128 v[138:141], v142 offset:2048
	ds_read_b128 v[142:145], v142 offset:3072
	s_add_u32 s0, s44, 0xb0000
	s_addc_u32 s1, s45, 0
	s_mov_b32 m0, s80
	v_lshl_add_u64 v[178:179], s[0:1], 0, v[0:1]
	ds_read_b128 v[146:149], v247 offset:32768
	ds_read_b128 v[150:153], v247 offset:33792
	ds_read_b128 v[154:157], v247 offset:34816
	ds_read_b128 v[158:161], v247 offset:35840
	ds_read_b128 v[162:165], v247 offset:36864
	ds_read_b128 v[166:169], v247 offset:37888
	ds_read_b128 v[170:173], v247 offset:38912
	ds_read_b128 v[174:177], v247 offset:39936
	global_load_lds_dwordx4 v[178:179], off
	v_lshl_add_u64 v[178:179], s[0:1], 0, v[204:205]
	s_mov_b32 m0, s81
	s_nop 0
	global_load_lds_dwordx4 v[178:179], off
	s_waitcnt lgkmcnt(8)
	s_setprio 1
	s_barrier
	s_waitcnt lgkmcnt(0)
	v_mfma_f32_16x16x32_bf16 v[126:129], v[130:133], v[146:149], v[126:129]
	v_mfma_f32_16x16x32_bf16 v[122:125], v[138:141], v[146:149], v[122:125]
	v_mfma_f32_16x16x32_bf16 v[118:121], v[130:133], v[154:157], v[118:121]
	v_mfma_f32_16x16x32_bf16 v[114:117], v[138:141], v[154:157], v[114:117]
	v_mfma_f32_16x16x32_bf16 v[110:113], v[130:133], v[162:165], v[110:113]
	v_mfma_f32_16x16x32_bf16 v[106:109], v[138:141], v[162:165], v[106:109]
	v_mfma_f32_16x16x32_bf16 v[102:105], v[130:133], v[170:173], v[102:105]
	v_mfma_f32_16x16x32_bf16 v[98:101], v[138:141], v[170:173], v[98:101]
	v_mfma_f32_16x16x32_bf16 v[126:129], v[134:137], v[150:153], v[126:129]
	v_mfma_f32_16x16x32_bf16 v[122:125], v[142:145], v[150:153], v[122:125]
	v_mfma_f32_16x16x32_bf16 v[118:121], v[134:137], v[158:161], v[118:121]
	v_mfma_f32_16x16x32_bf16 v[114:117], v[142:145], v[158:161], v[114:117]
	v_mfma_f32_16x16x32_bf16 v[110:113], v[134:137], v[166:169], v[110:113]
	v_mfma_f32_16x16x32_bf16 v[106:109], v[142:145], v[166:169], v[106:109]
	v_mfma_f32_16x16x32_bf16 v[102:105], v[134:137], v[174:177], v[102:105]
	v_mfma_f32_16x16x32_bf16 v[98:101], v[142:145], v[174:177], v[98:101]
	s_setprio 0
	s_barrier
	s_mov_b32 m0, s95
	v_add_u32_e32 v194, s37, v242
	v_lshl_add_u64 v[214:215], v[214:215], 0, s[88:89]
	ds_read_b128 v[178:181], v194
	ds_read_b128 v[182:185], v194 offset:1024
	ds_read_b128 v[186:189], v194 offset:2048
	ds_read_b128 v[194:197], v194 offset:3072
	global_load_lds_dwordx4 v[214:215], off
	v_lshl_add_u64 v[214:215], v[216:217], 0, s[88:89]
	s_mov_b32 m0, s16
	s_nop 0
	global_load_lds_dwordx4 v[214:215], off
	s_setprio 1
	s_barrier
	s_waitcnt lgkmcnt(0)
	v_mfma_f32_16x16x32_bf16 v[94:97], v[178:181], v[146:149], v[94:97]
	v_mfma_f32_16x16x32_bf16 v[90:93], v[186:189], v[146:149], v[90:93]
	v_mfma_f32_16x16x32_bf16 v[86:89], v[178:181], v[154:157], v[86:89]
	v_mfma_f32_16x16x32_bf16 v[82:85], v[186:189], v[154:157], v[82:85]
	v_mfma_f32_16x16x32_bf16 v[78:81], v[178:181], v[162:165], v[78:81]
	v_mfma_f32_16x16x32_bf16 v[74:77], v[186:189], v[162:165], v[74:77]
	v_mfma_f32_16x16x32_bf16 v[70:73], v[178:181], v[170:173], v[70:73]
	v_mfma_f32_16x16x32_bf16 v[66:69], v[186:189], v[170:173], v[66:69]
	v_mfma_f32_16x16x32_bf16 v[94:97], v[182:185], v[150:153], v[94:97]
	v_mfma_f32_16x16x32_bf16 v[90:93], v[194:197], v[150:153], v[90:93]
	v_mfma_f32_16x16x32_bf16 v[86:89], v[182:185], v[158:161], v[86:89]
	v_mfma_f32_16x16x32_bf16 v[82:85], v[194:197], v[158:161], v[82:85]
	v_mfma_f32_16x16x32_bf16 v[78:81], v[182:185], v[166:169], v[78:81]
	v_mfma_f32_16x16x32_bf16 v[74:77], v[194:197], v[166:169], v[74:77]
	v_mfma_f32_16x16x32_bf16 v[70:73], v[182:185], v[174:177], v[70:73]
	v_mfma_f32_16x16x32_bf16 v[66:69], v[194:197], v[174:177], v[66:69]
	s_setprio 0
	s_mov_b32 m0, s17
	v_lshl_add_u64 v[214:215], v[218:219], 0, s[88:89]
	s_barrier
	ds_read_b128 v[146:149], v247 offset:49152
	ds_read_b128 v[150:153], v247 offset:50176
	ds_read_b128 v[154:157], v247 offset:51200
	ds_read_b128 v[158:161], v247 offset:52224
	ds_read_b128 v[162:165], v247 offset:53248
	ds_read_b128 v[166:169], v247 offset:54272
	ds_read_b128 v[170:173], v247 offset:55296
	ds_read_b128 v[174:177], v247 offset:56320
	global_load_lds_dwordx4 v[214:215], off
	v_lshl_add_u64 v[214:215], v[220:221], 0, s[88:89]
	s_mov_b32 m0, s60
	s_nop 0
	global_load_lds_dwordx4 v[214:215], off
	s_setprio 1
	s_barrier
	s_waitcnt lgkmcnt(0)
	v_mfma_f32_16x16x32_bf16 v[62:65], v[130:133], v[146:149], v[62:65]
	v_mfma_f32_16x16x32_bf16 v[58:61], v[138:141], v[146:149], v[58:61]
	v_mfma_f32_16x16x32_bf16 v[54:57], v[130:133], v[154:157], v[54:57]
	v_mfma_f32_16x16x32_bf16 v[50:53], v[138:141], v[154:157], v[50:53]
	v_mfma_f32_16x16x32_bf16 v[46:49], v[130:133], v[162:165], v[46:49]
	v_mfma_f32_16x16x32_bf16 v[42:45], v[138:141], v[162:165], v[42:45]
	v_mfma_f32_16x16x32_bf16 v[38:41], v[130:133], v[170:173], v[38:41]
	v_mfma_f32_16x16x32_bf16 v[34:37], v[138:141], v[170:173], v[34:37]
	v_mfma_f32_16x16x32_bf16 v[62:65], v[134:137], v[150:153], v[62:65]
	v_mfma_f32_16x16x32_bf16 v[58:61], v[142:145], v[150:153], v[58:61]
	v_mfma_f32_16x16x32_bf16 v[54:57], v[134:137], v[158:161], v[54:57]
	v_mfma_f32_16x16x32_bf16 v[50:53], v[142:145], v[158:161], v[50:53]
	v_mfma_f32_16x16x32_bf16 v[46:49], v[134:137], v[166:169], v[46:49]
	v_mfma_f32_16x16x32_bf16 v[42:45], v[142:145], v[166:169], v[42:45]
	v_mfma_f32_16x16x32_bf16 v[38:41], v[134:137], v[174:177], v[38:41]
	v_mfma_f32_16x16x32_bf16 v[34:37], v[142:145], v[174:177], v[34:37]
	s_setprio 0
	s_barrier
	s_add_u32 s0, s34, 0xb0080
	s_addc_u32 s1, s35, 0
	s_mov_b32 m0, s2
	v_lshl_add_u64 v[130:131], s[0:1], 0, v[0:1]
	global_load_lds_dwordx4 v[130:131], off
	v_lshl_add_u64 v[130:131], s[0:1], 0, v[204:205]
	s_mov_b32 m0, s3
	s_nop 0
	global_load_lds_dwordx4 v[130:131], off
	s_waitcnt vmcnt(6)
	s_setprio 1
	s_barrier
	v_mfma_f32_16x16x32_bf16 v[30:33], v[178:181], v[146:149], v[30:33]
	v_mfma_f32_16x16x32_bf16 v[26:29], v[186:189], v[146:149], v[26:29]
	v_mfma_f32_16x16x32_bf16 v[22:25], v[178:181], v[154:157], v[22:25]
	v_mfma_f32_16x16x32_bf16 v[18:21], v[186:189], v[154:157], v[18:21]
	v_mfma_f32_16x16x32_bf16 v[14:17], v[178:181], v[162:165], v[14:17]
	v_mfma_f32_16x16x32_bf16 v[10:13], v[186:189], v[162:165], v[10:13]
	v_mfma_f32_16x16x32_bf16 v[6:9], v[178:181], v[170:173], v[6:9]
	v_mfma_f32_16x16x32_bf16 v[2:5], v[186:189], v[170:173], v[2:5]
	v_mfma_f32_16x16x32_bf16 v[30:33], v[182:185], v[150:153], v[30:33]
	v_mfma_f32_16x16x32_bf16 v[26:29], v[194:197], v[150:153], v[26:29]
	v_mfma_f32_16x16x32_bf16 v[22:25], v[182:185], v[158:161], v[22:25]
	v_mfma_f32_16x16x32_bf16 v[18:21], v[194:197], v[158:161], v[18:21]
	v_mfma_f32_16x16x32_bf16 v[14:17], v[182:185], v[166:169], v[14:17]
	v_mfma_f32_16x16x32_bf16 v[10:13], v[194:197], v[166:169], v[10:13]
	v_mfma_f32_16x16x32_bf16 v[6:9], v[182:185], v[174:177], v[6:9]
	v_mfma_f32_16x16x32_bf16 v[2:5], v[194:197], v[174:177], v[2:5]
	s_setprio 0
	s_add_u32 s25, s25, 0x100
	s_addc_u32 s26, s26, 0
	s_cmp_ge_i32 s19, s11
	s_mov_b64 s[14:15], s[20:21]
	s_mov_b32 s18, s19
	s_barrier
	s_cbranch_scc0 .LBB0_307
	v_readfirstlane_b32 s98, v191
	s_cmpk_gt_u32 s98, 0xff
	s_cbranch_scc1 .Lrl_e0_307
	s_barrier

.LBB0_705:
	v_add_u32_e32 v86, s61, v184
	ds_read_b128 v[74:77], v86
	ds_read_b128 v[78:81], v86 offset:1024
	ds_read_b128 v[82:85], v86 offset:2048
	ds_read_b128 v[86:89], v86 offset:3072
	s_add_u32 s0, s20, 0xfffc0080
	s_addc_u32 s1, s21, -1
	s_cmp_eq_u32 vcc_lo, 12
	s_cselect_b32 s51, s49, s1
	s_cselect_b32 s50, s53, s0
	s_cselect_b32 s35, s54, s95
	s_cselect_b32 s34, s55, s93
	v_lshl_add_u64 v[180:181], s[20:21], 0, v[172:173]
	s_add_i32 m0, s85, 0xc000
	ds_read_b128 v[146:149], v201
	ds_read_b128 v[150:153], v201 offset:1024
	ds_read_b128 v[154:157], v201 offset:2048
	ds_read_b128 v[158:161], v201 offset:3072
	ds_read_b128 v[162:165], v201 offset:4096
	ds_read_b128 v[166:169], v201 offset:5120
	ds_read_b128 v[176:179], v201 offset:6144
	ds_read_b128 v[194:197], v201 offset:7168
	global_load_lds_dwordx4 v[180:181], off
	v_lshl_add_u64 v[180:181], s[20:21], 0, v[174:175]
	s_add_i32 m0, s85, 0xe000
	s_nop 0
	global_load_lds_dwordx4 v[180:181], off
	s_waitcnt lgkmcnt(8)
	s_setprio 1
	s_barrier
	s_waitcnt lgkmcnt(0)
	v_mfma_f32_16x16x32_bf16 v[126:129], v[74:77], v[146:149], v[126:129]
	v_mfma_f32_16x16x32_bf16 v[46:49], v[82:85], v[146:149], v[46:49]
	v_mfma_f32_16x16x32_bf16 v[138:141], v[74:77], v[154:157], v[138:141]
	v_mfma_f32_16x16x32_bf16 v[58:61], v[82:85], v[154:157], v[58:61]
	v_mfma_f32_16x16x32_bf16 v[130:133], v[74:77], v[162:165], v[130:133]
	v_mfma_f32_16x16x32_bf16 v[50:53], v[82:85], v[162:165], v[50:53]
	v_mfma_f32_16x16x32_bf16 v[114:117], v[74:77], v[176:179], v[114:117]
	v_mfma_f32_16x16x32_bf16 v[34:37], v[82:85], v[176:179], v[34:37]
	v_mfma_f32_16x16x32_bf16 v[126:129], v[78:81], v[150:153], v[126:129]
	v_mfma_f32_16x16x32_bf16 v[46:49], v[86:89], v[150:153], v[46:49]
	v_mfma_f32_16x16x32_bf16 v[138:141], v[78:81], v[158:161], v[138:141]
	v_mfma_f32_16x16x32_bf16 v[58:61], v[86:89], v[158:161], v[58:61]
	v_mfma_f32_16x16x32_bf16 v[130:133], v[78:81], v[166:169], v[130:133]
	v_mfma_f32_16x16x32_bf16 v[50:53], v[86:89], v[166:169], v[50:53]
	v_mfma_f32_16x16x32_bf16 v[114:117], v[78:81], v[194:197], v[114:117]
	v_mfma_f32_16x16x32_bf16 v[34:37], v[86:89], v[194:197], v[34:37]
	s_setprio 0
	s_barrier
	v_add_u32_e32 v180, s19, v184
	s_mov_b32 m0, s62
	ds_read_b128 v[204:207], v180
	ds_read_b128 v[208:211], v180 offset:1024
	ds_read_b128 v[212:215], v180 offset:2048
	ds_read_b128 v[216:219], v180 offset:3072
	v_lshl_add_u64 v[180:181], s[34:35], 0, v[0:1]
	global_load_lds_dwordx4 v[180:181], off
	v_lshl_add_u64 v[220:221], s[34:35], 0, v[170:171]
	s_mov_b32 m0, s63
	s_nop 0
	global_load_lds_dwordx4 v[220:221], off
	s_setprio 1
	s_barrier
	s_waitcnt lgkmcnt(0)
	v_mfma_f32_16x16x32_bf16 v[142:145], v[204:207], v[146:149], v[142:145]
	v_mfma_f32_16x16x32_bf16 v[62:65], v[212:215], v[146:149], v[62:65]
	v_mfma_f32_16x16x32_bf16 v[134:137], v[204:207], v[154:157], v[134:137]
	v_mfma_f32_16x16x32_bf16 v[54:57], v[212:215], v[154:157], v[54:57]
	v_mfma_f32_16x16x32_bf16 v[122:125], v[204:207], v[162:165], v[122:125]
	v_mfma_f32_16x16x32_bf16 v[42:45], v[212:215], v[162:165], v[42:45]
	v_mfma_f32_16x16x32_bf16 v[118:121], v[204:207], v[176:179], v[118:121]
	v_mfma_f32_16x16x32_bf16 v[38:41], v[212:215], v[176:179], v[38:41]
	v_mfma_f32_16x16x32_bf16 v[142:145], v[208:211], v[150:153], v[142:145]
	v_mfma_f32_16x16x32_bf16 v[62:65], v[216:219], v[150:153], v[62:65]
	v_mfma_f32_16x16x32_bf16 v[134:137], v[208:211], v[158:161], v[134:137]
	v_mfma_f32_16x16x32_bf16 v[54:57], v[216:219], v[158:161], v[54:57]
	v_mfma_f32_16x16x32_bf16 v[122:125], v[208:211], v[166:169], v[122:125]
	v_mfma_f32_16x16x32_bf16 v[42:45], v[216:219], v[166:169], v[42:45]
	v_mfma_f32_16x16x32_bf16 v[118:121], v[208:211], v[194:197], v[118:121]
	v_mfma_f32_16x16x32_bf16 v[38:41], v[216:219], v[194:197], v[38:41]
	s_setprio 0
	s_mov_b32 m0, s85
	v_lshl_add_u64 v[222:223], s[50:51], 0, v[0:1]
	s_barrier
	ds_read_b128 v[146:149], v201 offset:16384
	ds_read_b128 v[150:153], v201 offset:17408
	ds_read_b128 v[154:157], v201 offset:18432
	ds_read_b128 v[158:161], v201 offset:19456
	ds_read_b128 v[162:165], v201 offset:20480
	ds_read_b128 v[166:169], v201 offset:21504
	ds_read_b128 v[176:179], v201 offset:22528
	ds_read_b128 v[194:197], v201 offset:23552
	global_load_lds_dwordx4 v[222:223], off
	v_lshl_add_u64 v[232:233], s[50:51], 0, v[170:171]
	s_mov_b32 m0, s86
	s_nop 0
	global_load_lds_dwordx4 v[232:233], off
	s_setprio 1
	s_barrier
	s_waitcnt lgkmcnt(0)
	v_mfma_f32_16x16x32_bf16 v[106:109], v[74:77], v[146:149], v[106:109]
	v_mfma_f32_16x16x32_bf16 v[30:33], v[82:85], v[146:149], v[30:33]
	v_mfma_f32_16x16x32_bf16 v[102:105], v[74:77], v[154:157], v[102:105]
	v_mfma_f32_16x16x32_bf16 v[22:25], v[82:85], v[154:157], v[22:25]
	v_mfma_f32_16x16x32_bf16 v[94:97], v[74:77], v[162:165], v[94:97]
	v_mfma_f32_16x16x32_bf16 v[14:17], v[82:85], v[162:165], v[14:17]
	v_mfma_f32_16x16x32_bf16 v[66:69], v[74:77], v[176:179], v[66:69]
	v_mfma_f32_16x16x32_bf16 v[2:5], v[82:85], v[176:179], v[2:5]
	v_mfma_f32_16x16x32_bf16 v[106:109], v[78:81], v[150:153], v[106:109]
	v_mfma_f32_16x16x32_bf16 v[30:33], v[86:89], v[150:153], v[30:33]
	v_mfma_f32_16x16x32_bf16 v[102:105], v[78:81], v[158:161], v[102:105]
	v_mfma_f32_16x16x32_bf16 v[22:25], v[86:89], v[158:161], v[22:25]
	v_mfma_f32_16x16x32_bf16 v[94:97], v[78:81], v[166:169], v[94:97]
	v_mfma_f32_16x16x32_bf16 v[14:17], v[86:89], v[166:169], v[14:17]
	v_mfma_f32_16x16x32_bf16 v[66:69], v[78:81], v[194:197], v[66:69]
	v_mfma_f32_16x16x32_bf16 v[2:5], v[86:89], v[194:197], v[2:5]
	s_setprio 0
	s_barrier
	s_add_u32 s0, s34, 0x40000
	s_addc_u32 s1, s35, 0
	s_mov_b32 m0, s90
	v_lshl_add_u64 v[74:75], s[0:1], 0, v[0:1]
	global_load_lds_dwordx4 v[74:75], off
	v_lshl_add_u64 v[74:75], s[0:1], 0, v[170:171]
	s_mov_b32 m0, s26
	s_nop 0
	global_load_lds_dwordx4 v[74:75], off
	s_waitcnt vmcnt(6)
	s_setprio 1
	s_barrier
	v_mfma_f32_16x16x32_bf16 v[26:29], v[212:215], v[146:149], v[26:29]
	v_mfma_f32_16x16x32_bf16 v[18:21], v[212:215], v[154:157], v[18:21]
	v_mfma_f32_16x16x32_bf16 v[10:13], v[212:215], v[162:165], v[10:13]
	v_mfma_f32_16x16x32_bf16 v[70:73], v[204:207], v[176:179], v[70:73]
	v_mfma_f32_16x16x32_bf16 v[6:9], v[212:215], v[176:179], v[6:9]
	v_mfma_f32_16x16x32_bf16 v[74:77], v[204:207], v[146:149], v[110:113]
	v_mfma_f32_16x16x32_bf16 v[26:29], v[216:219], v[150:153], v[26:29]
	v_mfma_f32_16x16x32_bf16 v[78:81], v[204:207], v[154:157], v[98:101]
	v_mfma_f32_16x16x32_bf16 v[18:21], v[216:219], v[158:161], v[18:21]
	v_mfma_f32_16x16x32_bf16 v[82:85], v[204:207], v[162:165], v[90:93]
	v_mfma_f32_16x16x32_bf16 v[10:13], v[216:219], v[166:169], v[10:13]
	v_mfma_f32_16x16x32_bf16 v[70:73], v[208:211], v[194:197], v[70:73]
	v_mfma_f32_16x16x32_bf16 v[6:9], v[216:219], v[194:197], v[6:9]
	v_mfma_f32_16x16x32_bf16 v[74:77], v[208:211], v[150:153], v[74:77]
	v_mfma_f32_16x16x32_bf16 v[78:81], v[208:211], v[158:161], v[78:81]
	v_mfma_f32_16x16x32_bf16 v[82:85], v[208:211], v[166:169], v[82:85]
	s_setprio 0
	v_add_u32_e32 v110, s36, v184
	s_barrier
	ds_read_b128 v[86:89], v110
	ds_read_b128 v[90:93], v110 offset:1024
	ds_read_b128 v[98:101], v110 offset:2048
	ds_read_b128 v[110:113], v110 offset:3072
	s_add_u32 s0, s50, 0x40000
	s_addc_u32 s1, s51, 0
	s_mov_b32 m0, s28
	v_lshl_add_u64 v[204:205], s[0:1], 0, v[0:1]
	ds_read_b128 v[146:149], v201 offset:32768
	ds_read_b128 v[150:153], v201 offset:33792
	ds_read_b128 v[154:157], v201 offset:34816
	ds_read_b128 v[158:161], v201 offset:35840
	ds_read_b128 v[162:165], v201 offset:36864
	ds_read_b128 v[166:169], v201 offset:37888
	ds_read_b128 v[176:179], v201 offset:38912
	ds_read_b128 v[194:197], v201 offset:39936
	global_load_lds_dwordx4 v[204:205], off
	v_lshl_add_u64 v[204:205], s[0:1], 0, v[170:171]
	s_mov_b32 m0, s30
	s_nop 0
	global_load_lds_dwordx4 v[204:205], off
	s_waitcnt lgkmcnt(8)
	s_setprio 1
	s_barrier
	s_waitcnt lgkmcnt(0)
	v_mfma_f32_16x16x32_bf16 v[126:129], v[86:89], v[146:149], v[126:129]
	v_mfma_f32_16x16x32_bf16 v[46:49], v[98:101], v[146:149], v[46:49]
	v_mfma_f32_16x16x32_bf16 v[138:141], v[86:89], v[154:157], v[138:141]
	v_mfma_f32_16x16x32_bf16 v[58:61], v[98:101], v[154:157], v[58:61]
	v_mfma_f32_16x16x32_bf16 v[130:133], v[86:89], v[162:165], v[130:133]
	v_mfma_f32_16x16x32_bf16 v[50:53], v[98:101], v[162:165], v[50:53]
	v_mfma_f32_16x16x32_bf16 v[114:117], v[86:89], v[176:179], v[114:117]
	v_mfma_f32_16x16x32_bf16 v[34:37], v[98:101], v[176:179], v[34:37]
	v_mfma_f32_16x16x32_bf16 v[126:129], v[90:93], v[150:153], v[126:129]
	v_mfma_f32_16x16x32_bf16 v[46:49], v[110:113], v[150:153], v[46:49]
	v_mfma_f32_16x16x32_bf16 v[138:141], v[90:93], v[158:161], v[138:141]
	v_mfma_f32_16x16x32_bf16 v[58:61], v[110:113], v[158:161], v[58:61]
	v_mfma_f32_16x16x32_bf16 v[130:133], v[90:93], v[166:169], v[130:133]
	v_mfma_f32_16x16x32_bf16 v[50:53], v[110:113], v[166:169], v[50:53]
	v_mfma_f32_16x16x32_bf16 v[114:117], v[90:93], v[194:197], v[114:117]
	v_mfma_f32_16x16x32_bf16 v[34:37], v[110:113], v[194:197], v[34:37]
	s_setprio 0
	s_barrier
	s_mov_b32 m0, s58
	v_add_u32_e32 v216, s8, v184
	v_lshl_add_u64 v[180:181], v[180:181], 0, s[88:89]
	ds_read_b128 v[204:207], v216
	ds_read_b128 v[208:211], v216 offset:1024
	ds_read_b128 v[212:215], v216 offset:2048
	ds_read_b128 v[216:219], v216 offset:3072
	global_load_lds_dwordx4 v[180:181], off
	v_lshl_add_u64 v[180:181], v[220:221], 0, s[88:89]
	s_mov_b32 m0, s38
	s_nop 0
	global_load_lds_dwordx4 v[180:181], off
	s_setprio 1
	s_barrier
	s_waitcnt lgkmcnt(0)
	v_mfma_f32_16x16x32_bf16 v[142:145], v[204:207], v[146:149], v[142:145]
	v_mfma_f32_16x16x32_bf16 v[62:65], v[212:215], v[146:149], v[62:65]
	v_mfma_f32_16x16x32_bf16 v[134:137], v[204:207], v[154:157], v[134:137]
	v_mfma_f32_16x16x32_bf16 v[54:57], v[212:215], v[154:157], v[54:57]
	v_mfma_f32_16x16x32_bf16 v[122:125], v[204:207], v[162:165], v[122:125]
	v_mfma_f32_16x16x32_bf16 v[42:45], v[212:215], v[162:165], v[42:45]
	v_mfma_f32_16x16x32_bf16 v[118:121], v[204:207], v[176:179], v[118:121]
	v_mfma_f32_16x16x32_bf16 v[38:41], v[212:215], v[176:179], v[38:41]
	v_mfma_f32_16x16x32_bf16 v[142:145], v[208:211], v[150:153], v[142:145]
	v_mfma_f32_16x16x32_bf16 v[62:65], v[216:219], v[150:153], v[62:65]
	v_mfma_f32_16x16x32_bf16 v[134:137], v[208:211], v[158:161], v[134:137]
	v_mfma_f32_16x16x32_bf16 v[54:57], v[216:219], v[158:161], v[54:57]
	v_mfma_f32_16x16x32_bf16 v[122:125], v[208:211], v[166:169], v[122:125]
	v_mfma_f32_16x16x32_bf16 v[42:45], v[216:219], v[166:169], v[42:45]
	v_mfma_f32_16x16x32_bf16 v[118:121], v[208:211], v[194:197], v[118:121]
	v_mfma_f32_16x16x32_bf16 v[38:41], v[216:219], v[194:197], v[38:41]
	s_setprio 0
	s_mov_b32 m0, s96
	v_lshl_add_u64 v[180:181], v[222:223], 0, s[88:89]
	s_barrier
	ds_read_b128 v[146:149], v201 offset:49152
	ds_read_b128 v[150:153], v201 offset:50176
	ds_read_b128 v[154:157], v201 offset:51200
	ds_read_b128 v[158:161], v201 offset:52224
	ds_read_b128 v[162:165], v201 offset:53248
	ds_read_b128 v[166:169], v201 offset:54272
	ds_read_b128 v[176:179], v201 offset:55296
	ds_read_b128 v[194:197], v201 offset:56320
	global_load_lds_dwordx4 v[180:181], off
	v_lshl_add_u64 v[180:181], v[232:233], 0, s[88:89]
	s_mov_b32 m0, s4
	s_nop 0
	global_load_lds_dwordx4 v[180:181], off
	s_setprio 1
	s_barrier
	s_waitcnt lgkmcnt(0)
	v_mfma_f32_16x16x32_bf16 v[106:109], v[86:89], v[146:149], v[106:109]
	v_mfma_f32_16x16x32_bf16 v[30:33], v[98:101], v[146:149], v[30:33]
	v_mfma_f32_16x16x32_bf16 v[102:105], v[86:89], v[154:157], v[102:105]
	v_mfma_f32_16x16x32_bf16 v[22:25], v[98:101], v[154:157], v[22:25]
	v_mfma_f32_16x16x32_bf16 v[94:97], v[86:89], v[162:165], v[94:97]
	v_mfma_f32_16x16x32_bf16 v[14:17], v[98:101], v[162:165], v[14:17]
	v_mfma_f32_16x16x32_bf16 v[66:69], v[86:89], v[176:179], v[66:69]
	v_mfma_f32_16x16x32_bf16 v[2:5], v[98:101], v[176:179], v[2:5]
	v_mfma_f32_16x16x32_bf16 v[106:109], v[90:93], v[150:153], v[106:109]
	v_mfma_f32_16x16x32_bf16 v[30:33], v[110:113], v[150:153], v[30:33]
	v_mfma_f32_16x16x32_bf16 v[102:105], v[90:93], v[158:161], v[102:105]
	v_mfma_f32_16x16x32_bf16 v[22:25], v[110:113], v[158:161], v[22:25]
	v_mfma_f32_16x16x32_bf16 v[94:97], v[90:93], v[166:169], v[94:97]
	v_mfma_f32_16x16x32_bf16 v[14:17], v[110:113], v[166:169], v[14:17]
	v_mfma_f32_16x16x32_bf16 v[66:69], v[90:93], v[194:197], v[66:69]
	v_mfma_f32_16x16x32_bf16 v[2:5], v[110:113], v[194:197], v[2:5]
	s_setprio 0
	s_barrier
	s_add_u32 s0, s34, 0x40080
	s_addc_u32 s1, s35, 0
	s_mov_b32 m0, s10
	v_lshl_add_u64 v[86:87], s[0:1], 0, v[0:1]
	global_load_lds_dwordx4 v[86:87], off
	v_lshl_add_u64 v[86:87], s[0:1], 0, v[170:171]
	s_mov_b32 m0, s11
	s_nop 0
	global_load_lds_dwordx4 v[86:87], off
	s_waitcnt vmcnt(6)
	s_setprio 1
	s_barrier
	v_mfma_f32_16x16x32_bf16 v[74:77], v[204:207], v[146:149], v[74:77]
	v_mfma_f32_16x16x32_bf16 v[110:113], v[208:211], v[150:153], v[74:77]
	v_mfma_f32_16x16x32_bf16 v[74:77], v[204:207], v[154:157], v[78:81]
	v_mfma_f32_16x16x32_bf16 v[26:29], v[212:215], v[146:149], v[26:29]
	v_mfma_f32_16x16x32_bf16 v[98:101], v[208:211], v[158:161], v[74:77]
	v_mfma_f32_16x16x32_bf16 v[18:21], v[212:215], v[154:157], v[18:21]
	v_mfma_f32_16x16x32_bf16 v[74:77], v[204:207], v[162:165], v[82:85]
	v_mfma_f32_16x16x32_bf16 v[10:13], v[212:215], v[162:165], v[10:13]
	v_mfma_f32_16x16x32_bf16 v[70:73], v[204:207], v[176:179], v[70:73]
	v_mfma_f32_16x16x32_bf16 v[6:9], v[212:215], v[176:179], v[6:9]
	v_mfma_f32_16x16x32_bf16 v[26:29], v[216:219], v[150:153], v[26:29]
	v_mfma_f32_16x16x32_bf16 v[18:21], v[216:219], v[158:161], v[18:21]
	v_mfma_f32_16x16x32_bf16 v[90:93], v[208:211], v[166:169], v[74:77]
	v_mfma_f32_16x16x32_bf16 v[10:13], v[216:219], v[166:169], v[10:13]
	v_mfma_f32_16x16x32_bf16 v[70:73], v[208:211], v[194:197], v[70:73]
	v_mfma_f32_16x16x32_bf16 v[6:9], v[216:219], v[194:197], v[6:9]
	s_setprio 0
	s_add_i32 vcc_lo, vcc_lo, 2
	s_add_u32 s20, s20, 0x100
	s_addc_u32 s21, s21, 0
	s_add_u32 s93, s93, 0x100
	s_addc_u32 s95, s95, 0
	s_cmp_gt_u32 vcc_lo, 13
	s_barrier
	s_cbranch_scc0 .LBB0_705
	s_mov_b32 s100, 0xbfb8aa3b
	v_lshl_or_b32 v180, s48, 7, v185
	v_ashrrev_i32_e32 v181, 31, v180
	v_lshlrev_b64 v[74:75], 2, v[180:181]
	v_lshl_add_u64 v[76:77], s[2:3], 0, v[74:75]
	v_lshl_add_u64 v[86:87], s[76:77], 0, v[74:75]
	v_lshl_add_u64 v[88:89], s[80:81], 0, v[74:75]
	v_lshl_add_u64 v[158:159], s[16:17], 0, v[74:75]
	global_load_dwordx4 v[82:85], v[76:77], off offset:16
	global_load_dwordx4 v[154:157], v[76:77], off
	global_load_dwordx4 v[78:81], v[86:87], off offset:16
	global_load_dwordx4 v[150:153], v[86:87], off
	s_nop 0
	global_load_dwordx4 v[74:77], v[88:89], off offset:16
	global_load_dwordx4 v[146:149], v[88:89], off
	s_nop 0
	global_load_dwordx4 v[86:89], v[158:159], off offset:16
	s_nop 0
	global_load_dwordx4 v[158:161], v[158:159], off
	v_readlane_b32 s0, v254, 24
	s_cmpk_gt_u32 s0, 0xff
	s_cbranch_scc1 .Lup_e0_skip
	s_barrier

.LBB0_780:
	v_add_u32_e32 v30, s15, v202
	ds_read_b128 v[18:21], v30
	ds_read_b128 v[22:25], v30 offset:1024
	ds_read_b128 v[26:29], v30 offset:2048
	ds_read_b128 v[30:33], v30 offset:3072
	s_add_u32 s0, s20, 0xfffc0080
	s_addc_u32 s1, s21, -1
	s_cmp_eq_u32 s28, 12
	s_cselect_b32 s51, s8, s1
	s_cselect_b32 s50, s10, s0
	s_cselect_b32 s35, s11, s26
	s_cselect_b32 s34, s24, s25
	v_lshl_add_u64 v[184:185], s[20:21], 0, v[180:181]
	s_add_i32 m0, s61, 0xc000
	ds_read_b128 v[34:37], v204
	ds_read_b128 v[38:41], v204 offset:1024
	ds_read_b128 v[58:61], v204 offset:2048
	ds_read_b128 v[62:65], v204 offset:3072
	ds_read_b128 v[66:69], v204 offset:4096
	ds_read_b128 v[70:73], v204 offset:5120
	ds_read_b128 v[74:77], v204 offset:6144
	ds_read_b128 v[78:81], v204 offset:7168
	global_load_lds_dwordx4 v[184:185], off
	v_lshl_add_u64 v[184:185], s[20:21], 0, v[182:183]
	s_add_i32 m0, s61, 0xe000
	s_nop 0
	global_load_lds_dwordx4 v[184:185], off
	s_waitcnt lgkmcnt(8)
	s_setprio 1
	s_barrier
	s_waitcnt lgkmcnt(0)
	v_mfma_f32_16x16x32_bf16 v[174:177], v[18:21], v[34:37], v[174:177]
	v_mfma_f32_16x16x32_bf16 v[170:173], v[26:29], v[34:37], v[170:173]
	v_mfma_f32_16x16x32_bf16 v[158:161], v[18:21], v[58:61], v[158:161]
	v_mfma_f32_16x16x32_bf16 v[154:157], v[26:29], v[58:61], v[154:157]
	v_mfma_f32_16x16x32_bf16 v[142:145], v[18:21], v[66:69], v[142:145]
	v_mfma_f32_16x16x32_bf16 v[138:141], v[26:29], v[66:69], v[138:141]
	v_mfma_f32_16x16x32_bf16 v[126:129], v[18:21], v[74:77], v[126:129]
	v_mfma_f32_16x16x32_bf16 v[122:125], v[26:29], v[74:77], v[122:125]
	v_mfma_f32_16x16x32_bf16 v[174:177], v[22:25], v[38:41], v[174:177]
	v_mfma_f32_16x16x32_bf16 v[170:173], v[30:33], v[38:41], v[170:173]
	v_mfma_f32_16x16x32_bf16 v[158:161], v[22:25], v[62:65], v[158:161]
	v_mfma_f32_16x16x32_bf16 v[154:157], v[30:33], v[62:65], v[154:157]
	v_mfma_f32_16x16x32_bf16 v[142:145], v[22:25], v[70:73], v[142:145]
	v_mfma_f32_16x16x32_bf16 v[138:141], v[30:33], v[70:73], v[138:141]
	v_mfma_f32_16x16x32_bf16 v[126:129], v[22:25], v[78:81], v[126:129]
	v_mfma_f32_16x16x32_bf16 v[122:125], v[30:33], v[78:81], v[122:125]
	s_setprio 0
	s_barrier
	v_add_u32_e32 v188, s63, v202
	s_mov_b32 m0, s55
	ds_read_b128 v[184:187], v188
	ds_read_b128 v[206:209], v188 offset:1024
	ds_read_b128 v[210:213], v188 offset:2048
	ds_read_b128 v[214:217], v188 offset:3072
	v_lshl_add_u64 v[188:189], s[34:35], 0, v[0:1]
	global_load_lds_dwordx4 v[188:189], off
	v_lshl_add_u64 v[222:223], s[34:35], 0, v[178:179]
	s_mov_b32 m0, s60
	s_nop 0
	global_load_lds_dwordx4 v[222:223], off
	s_setprio 1
	s_barrier
	s_waitcnt lgkmcnt(0)
	v_mfma_f32_16x16x32_bf16 v[166:169], v[184:187], v[34:37], v[166:169]
	v_mfma_f32_16x16x32_bf16 v[34:37], v[210:213], v[34:37], v[162:165]
	v_mfma_f32_16x16x32_bf16 v[166:169], v[206:209], v[38:41], v[166:169]
	v_mfma_f32_16x16x32_bf16 v[34:37], v[214:217], v[38:41], v[34:37]
	v_mfma_f32_16x16x32_bf16 v[38:41], v[184:187], v[58:61], v[150:153]
	v_mfma_f32_16x16x32_bf16 v[58:61], v[210:213], v[58:61], v[146:149]
	v_mfma_f32_16x16x32_bf16 v[38:41], v[206:209], v[62:65], v[38:41]
	v_mfma_f32_16x16x32_bf16 v[58:61], v[214:217], v[62:65], v[58:61]
	v_mfma_f32_16x16x32_bf16 v[62:65], v[184:187], v[66:69], v[134:137]
	v_mfma_f32_16x16x32_bf16 v[66:69], v[210:213], v[66:69], v[130:133]
	v_mfma_f32_16x16x32_bf16 v[62:65], v[206:209], v[70:73], v[62:65]
	v_mfma_f32_16x16x32_bf16 v[66:69], v[214:217], v[70:73], v[66:69]
	v_mfma_f32_16x16x32_bf16 v[70:73], v[184:187], v[74:77], v[118:121]
	v_mfma_f32_16x16x32_bf16 v[74:77], v[210:213], v[74:77], v[114:117]
	v_mfma_f32_16x16x32_bf16 v[70:73], v[206:209], v[78:81], v[70:73]
	v_mfma_f32_16x16x32_bf16 v[74:77], v[214:217], v[78:81], v[74:77]
	s_setprio 0
	s_mov_b32 m0, s61
	v_lshl_add_u64 v[250:251], s[50:51], 0, v[0:1]
	s_barrier
	ds_read_b128 v[78:81], v204 offset:16384
	ds_read_b128 v[114:117], v204 offset:17408
	ds_read_b128 v[118:121], v204 offset:18432
	ds_read_b128 v[130:133], v204 offset:19456
	ds_read_b128 v[134:137], v204 offset:20480
	ds_read_b128 v[146:149], v204 offset:21504
	ds_read_b128 v[150:153], v204 offset:22528
	ds_read_b128 v[162:165], v204 offset:23552
	global_load_lds_dwordx4 v[250:251], off
	v_lshl_add_u64 v[232:233], s[50:51], 0, v[178:179]
	s_mov_b32 m0, s62
	s_nop 0
	global_load_lds_dwordx4 v[232:233], off
	s_setprio 1
	s_barrier
	s_waitcnt lgkmcnt(0)
	v_mfma_f32_16x16x32_bf16 v[110:113], v[18:21], v[78:81], v[110:113]
	v_mfma_f32_16x16x32_bf16 v[106:109], v[26:29], v[78:81], v[106:109]
	v_mfma_f32_16x16x32_bf16 v[94:97], v[18:21], v[118:121], v[94:97]
	v_mfma_f32_16x16x32_bf16 v[90:93], v[26:29], v[118:121], v[90:93]
	v_mfma_f32_16x16x32_bf16 v[54:57], v[18:21], v[134:137], v[54:57]
	v_mfma_f32_16x16x32_bf16 v[50:53], v[26:29], v[134:137], v[50:53]
	v_mfma_f32_16x16x32_bf16 v[14:17], v[18:21], v[150:153], v[14:17]
	v_mfma_f32_16x16x32_bf16 v[10:13], v[26:29], v[150:153], v[10:13]
	v_mfma_f32_16x16x32_bf16 v[110:113], v[22:25], v[114:117], v[110:113]
	v_mfma_f32_16x16x32_bf16 v[106:109], v[30:33], v[114:117], v[106:109]
	v_mfma_f32_16x16x32_bf16 v[94:97], v[22:25], v[130:133], v[94:97]
	v_mfma_f32_16x16x32_bf16 v[90:93], v[30:33], v[130:133], v[90:93]
	v_mfma_f32_16x16x32_bf16 v[54:57], v[22:25], v[146:149], v[54:57]
	v_mfma_f32_16x16x32_bf16 v[50:53], v[30:33], v[146:149], v[50:53]
	v_mfma_f32_16x16x32_bf16 v[14:17], v[22:25], v[162:165], v[14:17]
	v_mfma_f32_16x16x32_bf16 v[10:13], v[30:33], v[162:165], v[10:13]
	s_setprio 0
	s_barrier
	s_add_u32 s0, s34, 0x40000
	s_addc_u32 s1, s35, 0
	s_mov_b32 m0, s66
	v_lshl_add_u64 v[18:19], s[0:1], 0, v[0:1]
	global_load_lds_dwordx4 v[18:19], off
	v_lshl_add_u64 v[18:19], s[0:1], 0, v[178:179]
	s_mov_b32 m0, s67
	s_nop 0
	global_load_lds_dwordx4 v[18:19], off
	s_waitcnt vmcnt(6)
	s_setprio 1
	s_barrier
	v_mfma_f32_16x16x32_bf16 v[46:49], v[184:187], v[134:137], v[46:49]
	v_mfma_f32_16x16x32_bf16 v[42:45], v[210:213], v[134:137], v[42:45]
	v_mfma_f32_16x16x32_bf16 v[6:9], v[184:187], v[150:153], v[6:9]
	v_mfma_f32_16x16x32_bf16 v[2:5], v[210:213], v[150:153], v[2:5]
	v_mfma_f32_16x16x32_bf16 v[18:21], v[184:187], v[78:81], v[102:105]
	v_mfma_f32_16x16x32_bf16 v[22:25], v[210:213], v[78:81], v[98:101]
	v_mfma_f32_16x16x32_bf16 v[26:29], v[184:187], v[118:121], v[86:89]
	v_mfma_f32_16x16x32_bf16 v[30:33], v[210:213], v[118:121], v[82:85]
	v_mfma_f32_16x16x32_bf16 v[46:49], v[206:209], v[146:149], v[46:49]
	v_mfma_f32_16x16x32_bf16 v[42:45], v[214:217], v[146:149], v[42:45]
	v_mfma_f32_16x16x32_bf16 v[6:9], v[206:209], v[162:165], v[6:9]
	v_mfma_f32_16x16x32_bf16 v[2:5], v[214:217], v[162:165], v[2:5]
	v_mfma_f32_16x16x32_bf16 v[18:21], v[206:209], v[114:117], v[18:21]
	v_mfma_f32_16x16x32_bf16 v[22:25], v[214:217], v[114:117], v[22:25]
	v_mfma_f32_16x16x32_bf16 v[26:29], v[206:209], v[130:133], v[26:29]
	v_mfma_f32_16x16x32_bf16 v[30:33], v[214:217], v[130:133], v[30:33]
	s_setprio 0
	v_add_u32_e32 v98, s72, v202
	s_barrier
	ds_read_b128 v[78:81], v98
	ds_read_b128 v[82:85], v98 offset:1024
	ds_read_b128 v[86:89], v98 offset:2048
	ds_read_b128 v[98:101], v98 offset:3072
	s_add_u32 s0, s50, 0x40000
	s_addc_u32 s1, s51, 0
	s_mov_b32 m0, s68
	v_lshl_add_u64 v[134:135], s[0:1], 0, v[0:1]
	ds_read_b128 v[102:105], v204 offset:32768
	ds_read_b128 v[114:117], v204 offset:33792
	ds_read_b128 v[118:121], v204 offset:34816
	ds_read_b128 v[130:133], v204 offset:35840
	ds_read_b128 v[184:187], v204 offset:36864
	ds_read_b128 v[206:209], v204 offset:37888
	ds_read_b128 v[210:213], v204 offset:38912
	ds_read_b128 v[214:217], v204 offset:39936
	global_load_lds_dwordx4 v[134:135], off
	v_lshl_add_u64 v[134:135], s[0:1], 0, v[178:179]
	s_mov_b32 m0, s69
	s_nop 0
	global_load_lds_dwordx4 v[134:135], off
	s_waitcnt lgkmcnt(8)
	s_setprio 1
	s_barrier
	s_waitcnt lgkmcnt(0)
	v_mfma_f32_16x16x32_bf16 v[134:137], v[78:81], v[102:105], v[174:177]
	v_mfma_f32_16x16x32_bf16 v[174:177], v[82:85], v[114:117], v[134:137]
	v_mfma_f32_16x16x32_bf16 v[134:137], v[86:89], v[102:105], v[170:173]
	v_mfma_f32_16x16x32_bf16 v[170:173], v[98:101], v[114:117], v[134:137]
	v_mfma_f32_16x16x32_bf16 v[134:137], v[78:81], v[118:121], v[158:161]
	v_mfma_f32_16x16x32_bf16 v[158:161], v[82:85], v[130:133], v[134:137]
	v_mfma_f32_16x16x32_bf16 v[134:137], v[86:89], v[118:121], v[154:157]
	v_mfma_f32_16x16x32_bf16 v[154:157], v[98:101], v[130:133], v[134:137]
	v_mfma_f32_16x16x32_bf16 v[134:137], v[78:81], v[184:187], v[142:145]
	v_mfma_f32_16x16x32_bf16 v[142:145], v[82:85], v[206:209], v[134:137]
	v_mfma_f32_16x16x32_bf16 v[134:137], v[86:89], v[184:187], v[138:141]
	v_mfma_f32_16x16x32_bf16 v[126:129], v[78:81], v[210:213], v[126:129]
	v_mfma_f32_16x16x32_bf16 v[122:125], v[86:89], v[210:213], v[122:125]
	v_mfma_f32_16x16x32_bf16 v[138:141], v[98:101], v[206:209], v[134:137]
	v_mfma_f32_16x16x32_bf16 v[126:129], v[82:85], v[214:217], v[126:129]
	v_mfma_f32_16x16x32_bf16 v[122:125], v[98:101], v[214:217], v[122:125]
	s_setprio 0
	s_barrier
	s_nop 0
	v_add_u32_e32 v134, s77, v202
	s_mov_b32 m0, s73
	ds_read_b128 v[218:221], v134
	ds_read_b128 v[242:245], v134 offset:1024
	ds_read_b128 v[246:249], v134 offset:2048
	ds_read_b128 v[194:197], v134 offset:3072
	v_lshl_add_u64 v[134:135], v[188:189], 0, s[88:89]
	global_load_lds_dwordx4 v[134:135], off
	v_lshl_add_u64 v[134:135], v[222:223], 0, s[88:89]
	s_mov_b32 m0, s74
	s_nop 0
	global_load_lds_dwordx4 v[134:135], off
	s_setprio 1
	s_barrier
	s_waitcnt lgkmcnt(0)
	v_mfma_f32_16x16x32_bf16 v[34:37], v[246:249], v[102:105], v[34:37]
	v_mfma_f32_16x16x32_bf16 v[162:165], v[194:197], v[114:117], v[34:37]
	v_mfma_f32_16x16x32_bf16 v[34:37], v[218:221], v[118:121], v[38:41]
	v_mfma_f32_16x16x32_bf16 v[150:153], v[242:245], v[130:133], v[34:37]
	v_mfma_f32_16x16x32_bf16 v[34:37], v[246:249], v[118:121], v[58:61]
	v_mfma_f32_16x16x32_bf16 v[134:137], v[218:221], v[102:105], v[166:169]
	v_mfma_f32_16x16x32_bf16 v[146:149], v[194:197], v[130:133], v[34:37]
	v_mfma_f32_16x16x32_bf16 v[34:37], v[218:221], v[184:187], v[62:65]
	v_mfma_f32_16x16x32_bf16 v[166:169], v[242:245], v[114:117], v[134:137]
	v_mfma_f32_16x16x32_bf16 v[134:137], v[242:245], v[206:209], v[34:37]
	v_mfma_f32_16x16x32_bf16 v[34:37], v[246:249], v[184:187], v[66:69]
	v_mfma_f32_16x16x32_bf16 v[130:133], v[194:197], v[206:209], v[34:37]
	v_mfma_f32_16x16x32_bf16 v[34:37], v[218:221], v[210:213], v[70:73]
	v_mfma_f32_16x16x32_bf16 v[118:121], v[242:245], v[214:217], v[34:37]
	v_mfma_f32_16x16x32_bf16 v[34:37], v[246:249], v[210:213], v[74:77]
	v_mfma_f32_16x16x32_bf16 v[114:117], v[194:197], v[214:217], v[34:37]
	s_setprio 0
	s_mov_b32 m0, s75
	v_lshl_add_u64 v[102:103], v[250:251], 0, s[88:89]
	s_barrier
	s_nop 2
	ds_read_b128 v[34:37], v204 offset:49152
	ds_read_b128 v[38:41], v204 offset:50176
	ds_read_b128 v[58:61], v204 offset:51200
	ds_read_b128 v[62:65], v204 offset:52224
	ds_read_b128 v[66:69], v204 offset:53248
	ds_read_b128 v[70:73], v204 offset:54272
	ds_read_b128 v[74:77], v204 offset:55296
	ds_read_b128 v[184:187], v204 offset:56320
	global_load_lds_dwordx4 v[102:103], off
	v_lshl_add_u64 v[102:103], v[232:233], 0, s[88:89]
	s_mov_b32 m0, s76
	s_nop 0
	global_load_lds_dwordx4 v[102:103], off
	s_setprio 1
	s_barrier
	s_waitcnt lgkmcnt(0)
	v_mfma_f32_16x16x32_bf16 v[102:105], v[78:81], v[34:37], v[110:113]
	v_mfma_f32_16x16x32_bf16 v[110:113], v[82:85], v[38:41], v[102:105]
	v_mfma_f32_16x16x32_bf16 v[102:105], v[86:89], v[34:37], v[106:109]
	v_mfma_f32_16x16x32_bf16 v[94:97], v[78:81], v[58:61], v[94:97]
	v_mfma_f32_16x16x32_bf16 v[90:93], v[86:89], v[58:61], v[90:93]
	v_mfma_f32_16x16x32_bf16 v[54:57], v[78:81], v[66:69], v[54:57]
	v_mfma_f32_16x16x32_bf16 v[50:53], v[86:89], v[66:69], v[50:53]
	v_mfma_f32_16x16x32_bf16 v[14:17], v[78:81], v[74:77], v[14:17]
	v_mfma_f32_16x16x32_bf16 v[10:13], v[86:89], v[74:77], v[10:13]
	v_mfma_f32_16x16x32_bf16 v[106:109], v[98:101], v[38:41], v[102:105]
	v_mfma_f32_16x16x32_bf16 v[94:97], v[82:85], v[62:65], v[94:97]
	v_mfma_f32_16x16x32_bf16 v[90:93], v[98:101], v[62:65], v[90:93]
	v_mfma_f32_16x16x32_bf16 v[54:57], v[82:85], v[70:73], v[54:57]
	v_mfma_f32_16x16x32_bf16 v[50:53], v[98:101], v[70:73], v[50:53]
	v_mfma_f32_16x16x32_bf16 v[14:17], v[82:85], v[184:187], v[14:17]
	v_mfma_f32_16x16x32_bf16 v[10:13], v[98:101], v[184:187], v[10:13]
	s_setprio 0
	s_barrier
	s_add_u32 s0, s34, 0x40080
	s_addc_u32 s1, s35, 0
	s_mov_b32 m0, s78
	v_lshl_add_u64 v[78:79], s[0:1], 0, v[0:1]
	global_load_lds_dwordx4 v[78:79], off
	v_lshl_add_u64 v[78:79], s[0:1], 0, v[178:179]
	s_mov_b32 m0, s79
	s_nop 0
	global_load_lds_dwordx4 v[78:79], off
	s_waitcnt vmcnt(6)
	s_setprio 1
	s_barrier
	v_mfma_f32_16x16x32_bf16 v[18:21], v[218:221], v[34:37], v[18:21]
	v_mfma_f32_16x16x32_bf16 v[102:105], v[242:245], v[38:41], v[18:21]
	v_mfma_f32_16x16x32_bf16 v[18:21], v[246:249], v[34:37], v[22:25]
	v_mfma_f32_16x16x32_bf16 v[98:101], v[194:197], v[38:41], v[18:21]
	v_mfma_f32_16x16x32_bf16 v[18:21], v[218:221], v[58:61], v[26:29]
	v_mfma_f32_16x16x32_bf16 v[86:89], v[242:245], v[62:65], v[18:21]
	v_mfma_f32_16x16x32_bf16 v[18:21], v[246:249], v[58:61], v[30:33]
	v_mfma_f32_16x16x32_bf16 v[82:85], v[194:197], v[62:65], v[18:21]
	v_mfma_f32_16x16x32_bf16 v[18:21], v[218:221], v[66:69], v[46:49]
	v_mfma_f32_16x16x32_bf16 v[46:49], v[242:245], v[70:73], v[18:21]
	v_mfma_f32_16x16x32_bf16 v[18:21], v[246:249], v[66:69], v[42:45]
	v_mfma_f32_16x16x32_bf16 v[6:9], v[218:221], v[74:77], v[6:9]
	v_mfma_f32_16x16x32_bf16 v[2:5], v[246:249], v[74:77], v[2:5]
	v_mfma_f32_16x16x32_bf16 v[42:45], v[194:197], v[70:73], v[18:21]
	v_mfma_f32_16x16x32_bf16 v[6:9], v[242:245], v[184:187], v[6:9]
	v_mfma_f32_16x16x32_bf16 v[2:5], v[194:197], v[184:187], v[2:5]
	s_setprio 0
	s_add_i32 s28, s28, 2
	s_add_u32 s20, s20, 0x100
	s_addc_u32 s21, s21, 0
	s_add_u32 s25, s25, 0x100
	s_addc_u32 s26, s26, 0
	s_cmp_gt_u32 s28, 13
	s_barrier
	s_cbranch_scc0 .LBB0_780
	v_readfirstlane_b32 s98, v191
	s_cmpk_gt_u32 s98, 0xff
	s_cbranch_scc1 .Lrl_e0_780
	s_barrier

.LBB0_794:
	v_add_u32_e32 v0, s10, v161
	ds_read_b128 v[122:125], v0
	ds_read_b128 v[126:129], v0 offset:1024
	ds_read_b128 v[130:133], v0 offset:2048
	ds_read_b128 v[134:137], v0 offset:3072
	s_add_u32 s0, s20, 0xfffc0080
	s_addc_u32 s1, s21, -1
	s_cmp_eq_u32 s71, 12
	s_cselect_b32 s49, s7, s1
	s_cselect_b32 s48, s67, s0
	s_cselect_b32 s35, s3, s70
	s_cselect_b32 s34, s68, s69
	v_lshl_add_u64 v[158:159], s[20:21], 0, v[150:151]
	s_add_i32 m0, s24, 0xc000
	ds_read_b128 v[154:157], v163
	ds_read_b128 v[164:167], v163 offset:1024
	ds_read_b128 v[168:171], v163 offset:2048
	ds_read_b128 v[172:175], v163 offset:3072
	ds_read_b128 v[176:179], v163 offset:4096
	ds_read_b128 v[180:183], v163 offset:5120
	ds_read_b128 v[184:187], v163 offset:6144
	ds_read_b128 v[202:205], v163 offset:7168
	global_load_lds_dwordx4 v[158:159], off
	v_lshl_add_u64 v[158:159], s[20:21], 0, v[152:153]
	s_add_i32 m0, s24, 0xe000
	s_nop 0
	global_load_lds_dwordx4 v[158:159], off
	s_waitcnt lgkmcnt(8)
	s_setprio 1
	s_barrier
	s_waitcnt lgkmcnt(0)
	v_mfma_f32_16x16x32_bf16 v[142:145], v[122:125], v[154:157], v[142:145]
	v_mfma_f32_16x16x32_bf16 v[138:141], v[130:133], v[154:157], v[138:141]
	v_mfma_f32_16x16x32_bf16 v[110:113], v[122:125], v[168:171], v[110:113]
	v_mfma_f32_16x16x32_bf16 v[106:109], v[130:133], v[168:171], v[106:109]
	v_mfma_f32_16x16x32_bf16 v[94:97], v[122:125], v[176:179], v[94:97]
	v_mfma_f32_16x16x32_bf16 v[90:93], v[130:133], v[176:179], v[90:93]
	v_mfma_f32_16x16x32_bf16 v[78:81], v[122:125], v[184:187], v[78:81]
	v_mfma_f32_16x16x32_bf16 v[74:77], v[130:133], v[184:187], v[74:77]
	v_mfma_f32_16x16x32_bf16 v[142:145], v[126:129], v[164:167], v[142:145]
	v_mfma_f32_16x16x32_bf16 v[138:141], v[134:137], v[164:167], v[138:141]
	v_mfma_f32_16x16x32_bf16 v[110:113], v[126:129], v[172:175], v[110:113]
	v_mfma_f32_16x16x32_bf16 v[106:109], v[134:137], v[172:175], v[106:109]
	v_mfma_f32_16x16x32_bf16 v[94:97], v[126:129], v[180:183], v[94:97]
	v_mfma_f32_16x16x32_bf16 v[90:93], v[134:137], v[180:183], v[90:93]
	v_mfma_f32_16x16x32_bf16 v[78:81], v[126:129], v[202:205], v[78:81]
	v_mfma_f32_16x16x32_bf16 v[74:77], v[134:137], v[202:205], v[74:77]
	s_setprio 0
	s_barrier
	s_mov_b32 m0, s11
	v_add_u32_e32 v0, s26, v161
	v_lshl_add_u64 v[158:159], s[34:35], 0, v[148:149]
	ds_read_b128 v[206:209], v0
	ds_read_b128 v[210:213], v0 offset:1024
	ds_read_b128 v[214:217], v0 offset:2048
	ds_read_b128 v[218:221], v0 offset:3072
	global_load_lds_dwordx4 v[158:159], off
	v_lshl_add_u64 v[188:189], s[34:35], 0, v[146:147]
	s_mov_b32 m0, s19
	s_nop 0
	global_load_lds_dwordx4 v[188:189], off
	s_setprio 1
	s_barrier
	s_waitcnt lgkmcnt(0)
	v_mfma_f32_16x16x32_bf16 v[118:121], v[206:209], v[154:157], v[118:121]
	v_mfma_f32_16x16x32_bf16 v[114:117], v[214:217], v[154:157], v[114:117]
	v_mfma_f32_16x16x32_bf16 v[102:105], v[206:209], v[168:171], v[102:105]
	v_mfma_f32_16x16x32_bf16 v[98:101], v[214:217], v[168:171], v[98:101]
	v_mfma_f32_16x16x32_bf16 v[86:89], v[206:209], v[176:179], v[86:89]
	v_mfma_f32_16x16x32_bf16 v[82:85], v[214:217], v[176:179], v[82:85]
	v_mfma_f32_16x16x32_bf16 v[70:73], v[206:209], v[184:187], v[70:73]
	v_mfma_f32_16x16x32_bf16 v[66:69], v[214:217], v[184:187], v[66:69]
	v_mfma_f32_16x16x32_bf16 v[118:121], v[210:213], v[164:167], v[118:121]
	v_mfma_f32_16x16x32_bf16 v[114:117], v[218:221], v[164:167], v[114:117]
	v_mfma_f32_16x16x32_bf16 v[102:105], v[210:213], v[172:175], v[102:105]
	v_mfma_f32_16x16x32_bf16 v[98:101], v[218:221], v[172:175], v[98:101]
	v_mfma_f32_16x16x32_bf16 v[86:89], v[210:213], v[180:183], v[86:89]
	v_mfma_f32_16x16x32_bf16 v[82:85], v[218:221], v[180:183], v[82:85]
	v_mfma_f32_16x16x32_bf16 v[70:73], v[210:213], v[202:205], v[70:73]
	v_mfma_f32_16x16x32_bf16 v[66:69], v[218:221], v[202:205], v[66:69]
	s_setprio 0
	s_mov_b32 m0, s24
	v_lshl_add_u64 v[194:195], s[48:49], 0, v[148:149]
	s_barrier
	ds_read_b128 v[154:157], v163 offset:16384
	ds_read_b128 v[164:167], v163 offset:17408
	ds_read_b128 v[168:171], v163 offset:18432
	ds_read_b128 v[172:175], v163 offset:19456
	ds_read_b128 v[176:179], v163 offset:20480
	ds_read_b128 v[180:183], v163 offset:21504
	ds_read_b128 v[184:187], v163 offset:22528
	ds_read_b128 v[202:205], v163 offset:23552
	global_load_lds_dwordx4 v[194:195], off
	v_lshl_add_u64 v[196:197], s[48:49], 0, v[146:147]
	s_mov_b32 m0, s25
	s_nop 0
	global_load_lds_dwordx4 v[196:197], off
	s_setprio 1
	s_barrier
	s_waitcnt lgkmcnt(0)
	v_mfma_f32_16x16x32_bf16 v[62:65], v[122:125], v[154:157], v[62:65]
	v_mfma_f32_16x16x32_bf16 v[58:61], v[130:133], v[154:157], v[58:61]
	v_mfma_f32_16x16x32_bf16 v[46:49], v[122:125], v[168:171], v[46:49]
	v_mfma_f32_16x16x32_bf16 v[42:45], v[130:133], v[168:171], v[42:45]
	v_mfma_f32_16x16x32_bf16 v[30:33], v[122:125], v[176:179], v[30:33]
	v_mfma_f32_16x16x32_bf16 v[26:29], v[130:133], v[176:179], v[26:29]
	v_mfma_f32_16x16x32_bf16 v[14:17], v[122:125], v[184:187], v[14:17]
	v_mfma_f32_16x16x32_bf16 v[10:13], v[130:133], v[184:187], v[10:13]
	v_mfma_f32_16x16x32_bf16 v[62:65], v[126:129], v[164:167], v[62:65]
	v_mfma_f32_16x16x32_bf16 v[58:61], v[134:137], v[164:167], v[58:61]
	v_mfma_f32_16x16x32_bf16 v[46:49], v[126:129], v[172:175], v[46:49]
	v_mfma_f32_16x16x32_bf16 v[42:45], v[134:137], v[172:175], v[42:45]
	v_mfma_f32_16x16x32_bf16 v[30:33], v[126:129], v[180:183], v[30:33]
	v_mfma_f32_16x16x32_bf16 v[26:29], v[134:137], v[180:183], v[26:29]
	v_mfma_f32_16x16x32_bf16 v[14:17], v[126:129], v[202:205], v[14:17]
	v_mfma_f32_16x16x32_bf16 v[10:13], v[134:137], v[202:205], v[10:13]
	s_setprio 0
	s_barrier
	s_add_u32 s0, s34, 0x40000
	s_addc_u32 s1, s35, 0
	s_mov_b32 m0, s28
	v_lshl_add_u64 v[122:123], s[0:1], 0, v[148:149]
	global_load_lds_dwordx4 v[122:123], off
	v_lshl_add_u64 v[122:123], s[0:1], 0, v[146:147]
	s_mov_b32 m0, s29
	s_nop 0
	global_load_lds_dwordx4 v[122:123], off
	s_waitcnt vmcnt(6)
	s_setprio 1
	s_barrier
	v_mfma_f32_16x16x32_bf16 v[54:57], v[206:209], v[154:157], v[54:57]
	v_mfma_f32_16x16x32_bf16 v[50:53], v[214:217], v[154:157], v[50:53]
	v_mfma_f32_16x16x32_bf16 v[38:41], v[206:209], v[168:171], v[38:41]
	v_mfma_f32_16x16x32_bf16 v[34:37], v[214:217], v[168:171], v[34:37]
	v_mfma_f32_16x16x32_bf16 v[22:25], v[206:209], v[176:179], v[22:25]
	v_mfma_f32_16x16x32_bf16 v[18:21], v[214:217], v[176:179], v[18:21]
	v_mfma_f32_16x16x32_bf16 v[6:9], v[206:209], v[184:187], v[6:9]
	v_mfma_f32_16x16x32_bf16 v[2:5], v[214:217], v[184:187], v[2:5]
	v_mfma_f32_16x16x32_bf16 v[54:57], v[210:213], v[164:167], v[54:57]
	v_mfma_f32_16x16x32_bf16 v[50:53], v[218:221], v[164:167], v[50:53]
	v_mfma_f32_16x16x32_bf16 v[38:41], v[210:213], v[172:175], v[38:41]
	v_mfma_f32_16x16x32_bf16 v[34:37], v[218:221], v[172:175], v[34:37]
	v_mfma_f32_16x16x32_bf16 v[22:25], v[210:213], v[180:183], v[22:25]
	v_mfma_f32_16x16x32_bf16 v[18:21], v[218:221], v[180:183], v[18:21]
	v_mfma_f32_16x16x32_bf16 v[6:9], v[210:213], v[202:205], v[6:9]
	v_mfma_f32_16x16x32_bf16 v[2:5], v[218:221], v[202:205], v[2:5]
	s_setprio 0
	v_add_u32_e32 v0, s43, v161
	s_barrier
	ds_read_b128 v[122:125], v0
	ds_read_b128 v[126:129], v0 offset:1024
	ds_read_b128 v[130:133], v0 offset:2048
	ds_read_b128 v[134:137], v0 offset:3072
	s_add_u32 s0, s48, 0x40000
	s_addc_u32 s1, s49, 0
	s_mov_b32 m0, s30
	v_lshl_add_u64 v[206:207], s[0:1], 0, v[148:149]
	ds_read_b128 v[154:157], v163 offset:32768
	ds_read_b128 v[164:167], v163 offset:33792
	ds_read_b128 v[168:171], v163 offset:34816
	ds_read_b128 v[172:175], v163 offset:35840
	ds_read_b128 v[176:179], v163 offset:36864
	ds_read_b128 v[180:183], v163 offset:37888
	ds_read_b128 v[184:187], v163 offset:38912
	ds_read_b128 v[202:205], v163 offset:39936
	global_load_lds_dwordx4 v[206:207], off
	v_lshl_add_u64 v[206:207], s[0:1], 0, v[146:147]
	s_mov_b32 m0, s36
	s_nop 0
	global_load_lds_dwordx4 v[206:207], off
	s_waitcnt lgkmcnt(8)
	s_setprio 1
	s_barrier
	s_waitcnt lgkmcnt(0)
	v_mfma_f32_16x16x32_bf16 v[142:145], v[122:125], v[154:157], v[142:145]
	v_mfma_f32_16x16x32_bf16 v[138:141], v[130:133], v[154:157], v[138:141]
	v_mfma_f32_16x16x32_bf16 v[110:113], v[122:125], v[168:171], v[110:113]
	v_mfma_f32_16x16x32_bf16 v[106:109], v[130:133], v[168:171], v[106:109]
	v_mfma_f32_16x16x32_bf16 v[94:97], v[122:125], v[176:179], v[94:97]
	v_mfma_f32_16x16x32_bf16 v[90:93], v[130:133], v[176:179], v[90:93]
	v_mfma_f32_16x16x32_bf16 v[78:81], v[122:125], v[184:187], v[78:81]
	v_mfma_f32_16x16x32_bf16 v[74:77], v[130:133], v[184:187], v[74:77]
	v_mfma_f32_16x16x32_bf16 v[142:145], v[126:129], v[164:167], v[142:145]
	v_mfma_f32_16x16x32_bf16 v[138:141], v[134:137], v[164:167], v[138:141]
	v_mfma_f32_16x16x32_bf16 v[110:113], v[126:129], v[172:175], v[110:113]
	v_mfma_f32_16x16x32_bf16 v[106:109], v[134:137], v[172:175], v[106:109]
	v_mfma_f32_16x16x32_bf16 v[94:97], v[126:129], v[180:183], v[94:97]
	v_mfma_f32_16x16x32_bf16 v[90:93], v[134:137], v[180:183], v[90:93]
	v_mfma_f32_16x16x32_bf16 v[78:81], v[126:129], v[202:205], v[78:81]
	v_mfma_f32_16x16x32_bf16 v[74:77], v[134:137], v[202:205], v[74:77]
	s_setprio 0
	s_barrier
	s_mov_b32 m0, s50
	v_add_u32_e32 v0, s58, v161
	v_lshl_add_u64 v[158:159], v[158:159], 0, s[88:89]
	ds_read_b128 v[206:209], v0
	ds_read_b128 v[210:213], v0 offset:1024
	ds_read_b128 v[214:217], v0 offset:2048
	ds_read_b128 v[218:221], v0 offset:3072
	global_load_lds_dwordx4 v[158:159], off
	v_lshl_add_u64 v[158:159], v[188:189], 0, s[88:89]
	s_mov_b32 m0, s51
	s_nop 0
	global_load_lds_dwordx4 v[158:159], off
	s_setprio 1
	s_barrier
	s_waitcnt lgkmcnt(0)
	v_mfma_f32_16x16x32_bf16 v[118:121], v[206:209], v[154:157], v[118:121]
	v_mfma_f32_16x16x32_bf16 v[114:117], v[214:217], v[154:157], v[114:117]
	v_mfma_f32_16x16x32_bf16 v[102:105], v[206:209], v[168:171], v[102:105]
	v_mfma_f32_16x16x32_bf16 v[98:101], v[214:217], v[168:171], v[98:101]
	v_mfma_f32_16x16x32_bf16 v[86:89], v[206:209], v[176:179], v[86:89]
	v_mfma_f32_16x16x32_bf16 v[82:85], v[214:217], v[176:179], v[82:85]
	v_mfma_f32_16x16x32_bf16 v[70:73], v[206:209], v[184:187], v[70:73]
	v_mfma_f32_16x16x32_bf16 v[66:69], v[214:217], v[184:187], v[66:69]
	v_mfma_f32_16x16x32_bf16 v[118:121], v[210:213], v[164:167], v[118:121]
	v_mfma_f32_16x16x32_bf16 v[114:117], v[218:221], v[164:167], v[114:117]
	v_mfma_f32_16x16x32_bf16 v[102:105], v[210:213], v[172:175], v[102:105]
	v_mfma_f32_16x16x32_bf16 v[98:101], v[218:221], v[172:175], v[98:101]
	v_mfma_f32_16x16x32_bf16 v[86:89], v[210:213], v[180:183], v[86:89]
	v_mfma_f32_16x16x32_bf16 v[82:85], v[218:221], v[180:183], v[82:85]
	v_mfma_f32_16x16x32_bf16 v[70:73], v[210:213], v[202:205], v[70:73]
	v_mfma_f32_16x16x32_bf16 v[66:69], v[218:221], v[202:205], v[66:69]
	s_setprio 0
	s_mov_b32 m0, s54
	v_lshl_add_u64 v[158:159], v[194:195], 0, s[88:89]
	s_barrier
	ds_read_b128 v[154:157], v163 offset:49152
	ds_read_b128 v[164:167], v163 offset:50176
	ds_read_b128 v[168:171], v163 offset:51200
	ds_read_b128 v[172:175], v163 offset:52224
	ds_read_b128 v[176:179], v163 offset:53248
	ds_read_b128 v[180:183], v163 offset:54272
	ds_read_b128 v[184:187], v163 offset:55296
	ds_read_b128 v[202:205], v163 offset:56320
	global_load_lds_dwordx4 v[158:159], off
	v_lshl_add_u64 v[158:159], v[196:197], 0, s[88:89]
	s_mov_b32 m0, s55
	s_nop 0
	global_load_lds_dwordx4 v[158:159], off
	s_setprio 1
	s_barrier
	s_waitcnt lgkmcnt(0)
	v_mfma_f32_16x16x32_bf16 v[62:65], v[122:125], v[154:157], v[62:65]
	v_mfma_f32_16x16x32_bf16 v[58:61], v[130:133], v[154:157], v[58:61]
	v_mfma_f32_16x16x32_bf16 v[46:49], v[122:125], v[168:171], v[46:49]
	v_mfma_f32_16x16x32_bf16 v[42:45], v[130:133], v[168:171], v[42:45]
	v_mfma_f32_16x16x32_bf16 v[30:33], v[122:125], v[176:179], v[30:33]
	v_mfma_f32_16x16x32_bf16 v[26:29], v[130:133], v[176:179], v[26:29]
	v_mfma_f32_16x16x32_bf16 v[14:17], v[122:125], v[184:187], v[14:17]
	v_mfma_f32_16x16x32_bf16 v[10:13], v[130:133], v[184:187], v[10:13]
	v_mfma_f32_16x16x32_bf16 v[62:65], v[126:129], v[164:167], v[62:65]
	v_mfma_f32_16x16x32_bf16 v[58:61], v[134:137], v[164:167], v[58:61]
	v_mfma_f32_16x16x32_bf16 v[46:49], v[126:129], v[172:175], v[46:49]
	v_mfma_f32_16x16x32_bf16 v[42:45], v[134:137], v[172:175], v[42:45]
	v_mfma_f32_16x16x32_bf16 v[30:33], v[126:129], v[180:183], v[30:33]
	v_mfma_f32_16x16x32_bf16 v[26:29], v[134:137], v[180:183], v[26:29]
	v_mfma_f32_16x16x32_bf16 v[14:17], v[126:129], v[202:205], v[14:17]
	v_mfma_f32_16x16x32_bf16 v[10:13], v[134:137], v[202:205], v[10:13]
	s_setprio 0
	s_barrier
	s_add_u32 s0, s34, 0x40080
	s_addc_u32 s1, s35, 0
	s_mov_b32 m0, s60
	v_lshl_add_u64 v[122:123], s[0:1], 0, v[148:149]
	global_load_lds_dwordx4 v[122:123], off
	v_lshl_add_u64 v[122:123], s[0:1], 0, v[146:147]
	s_mov_b32 m0, s61
	s_nop 0
	global_load_lds_dwordx4 v[122:123], off
	s_waitcnt vmcnt(6)
	s_setprio 1
	s_barrier
	v_mfma_f32_16x16x32_bf16 v[54:57], v[206:209], v[154:157], v[54:57]
	v_mfma_f32_16x16x32_bf16 v[50:53], v[214:217], v[154:157], v[50:53]
	v_mfma_f32_16x16x32_bf16 v[38:41], v[206:209], v[168:171], v[38:41]
	v_mfma_f32_16x16x32_bf16 v[34:37], v[214:217], v[168:171], v[34:37]
	v_mfma_f32_16x16x32_bf16 v[22:25], v[206:209], v[176:179], v[22:25]
	v_mfma_f32_16x16x32_bf16 v[18:21], v[214:217], v[176:179], v[18:21]
	v_mfma_f32_16x16x32_bf16 v[6:9], v[206:209], v[184:187], v[6:9]
	v_mfma_f32_16x16x32_bf16 v[2:5], v[214:217], v[184:187], v[2:5]
	v_mfma_f32_16x16x32_bf16 v[54:57], v[210:213], v[164:167], v[54:57]
	v_mfma_f32_16x16x32_bf16 v[50:53], v[218:221], v[164:167], v[50:53]
	v_mfma_f32_16x16x32_bf16 v[38:41], v[210:213], v[172:175], v[38:41]
	v_mfma_f32_16x16x32_bf16 v[34:37], v[218:221], v[172:175], v[34:37]
	v_mfma_f32_16x16x32_bf16 v[22:25], v[210:213], v[180:183], v[22:25]
	v_mfma_f32_16x16x32_bf16 v[18:21], v[218:221], v[180:183], v[18:21]
	v_mfma_f32_16x16x32_bf16 v[6:9], v[210:213], v[202:205], v[6:9]
	v_mfma_f32_16x16x32_bf16 v[2:5], v[218:221], v[202:205], v[2:5]
	s_setprio 0
	s_add_i32 s71, s71, 2
	s_add_u32 s20, s20, 0x100
	s_addc_u32 s21, s21, 0
	s_add_u32 s69, s69, 0x100
	s_addc_u32 s70, s70, 0
	s_cmp_gt_u32 s71, 13
	s_barrier
	s_cbranch_scc0 .LBB0_794
	v_readfirstlane_b32 s98, v191
	s_cmpk_gt_u32 s98, 0xff
	s_cbranch_scc1 .Lrl_e0_794
	s_barrier

.LBB0_814:
	v_add_u32_e32 v152, s19, v136
	ds_read_b128 v[138:141], v152
	ds_read_b128 v[142:145], v152 offset:1024
	ds_read_b128 v[148:151], v152 offset:2048
	ds_read_b128 v[162:165], v152 offset:3072
	s_add_i32 s70, s70, 2
	s_cmp_lg_u32 s69, s20
	s_cselect_b32 s1, s20, 0
	s_cselect_b32 s0, s21, 0
	s_add_u32 s34, s16, s1
	s_addc_u32 s35, s17, s0
	s_add_u32 s42, s14, s1
	s_addc_u32 s43, s15, s0
	v_lshl_add_u64 v[152:153], v[134:135], 0, s[20:21]
	v_lshl_add_u64 v[152:153], v[152:153], 0, s[76:77]
	s_add_i32 m0, s52, 0xc000
	ds_read_b128 v[166:169], v137
	ds_read_b128 v[170:173], v137 offset:1024
	ds_read_b128 v[174:177], v137 offset:2048
	ds_read_b128 v[178:181], v137 offset:3072
	ds_read_b128 v[182:185], v137 offset:4096
	ds_read_b128 v[186:189], v137 offset:5120
	ds_read_b128 v[202:205], v137 offset:6144
	ds_read_b128 v[206:209], v137 offset:7168
	global_load_lds_dwordx4 v[152:153], off
	v_lshl_add_u64 v[152:153], v[132:133], 0, s[20:21]
	v_lshl_add_u64 v[152:153], v[152:153], 0, s[76:77]
	s_add_i32 m0, s52, 0xe000
	s_nop 0
	global_load_lds_dwordx4 v[152:153], off
	s_waitcnt lgkmcnt(8)
	s_setprio 1
	s_barrier
	s_waitcnt lgkmcnt(0)
	v_mfma_f32_16x16x32_bf16 v[126:129], v[138:141], v[166:169], v[126:129]
	v_mfma_f32_16x16x32_bf16 v[122:125], v[148:151], v[166:169], v[122:125]
	v_mfma_f32_16x16x32_bf16 v[118:121], v[138:141], v[174:177], v[118:121]
	v_mfma_f32_16x16x32_bf16 v[114:117], v[148:151], v[174:177], v[114:117]
	v_mfma_f32_16x16x32_bf16 v[110:113], v[138:141], v[182:185], v[110:113]
	v_mfma_f32_16x16x32_bf16 v[106:109], v[148:151], v[182:185], v[106:109]
	v_mfma_f32_16x16x32_bf16 v[102:105], v[138:141], v[202:205], v[102:105]
	v_mfma_f32_16x16x32_bf16 v[98:101], v[148:151], v[202:205], v[98:101]
	v_mfma_f32_16x16x32_bf16 v[126:129], v[142:145], v[170:173], v[126:129]
	v_mfma_f32_16x16x32_bf16 v[122:125], v[162:165], v[170:173], v[122:125]
	v_mfma_f32_16x16x32_bf16 v[118:121], v[142:145], v[178:181], v[118:121]
	v_mfma_f32_16x16x32_bf16 v[114:117], v[162:165], v[178:181], v[114:117]
	v_mfma_f32_16x16x32_bf16 v[110:113], v[142:145], v[186:189], v[110:113]
	v_mfma_f32_16x16x32_bf16 v[106:109], v[162:165], v[186:189], v[106:109]
	v_mfma_f32_16x16x32_bf16 v[102:105], v[142:145], v[206:209], v[102:105]
	v_mfma_f32_16x16x32_bf16 v[98:101], v[162:165], v[206:209], v[98:101]
	s_setprio 0
	s_barrier
	v_add_u32_e32 v152, s24, v136
	s_mov_b32 m0, s50
	ds_read_b128 v[210:213], v152
	ds_read_b128 v[214:217], v152 offset:1024
	ds_read_b128 v[218:221], v152 offset:2048
	ds_read_b128 v[242:245], v152 offset:3072
	v_lshl_add_u64 v[152:153], s[42:43], 0, v[0:1]
	global_load_lds_dwordx4 v[152:153], off
	v_lshl_add_u64 v[194:195], s[42:43], 0, v[130:131]
	s_mov_b32 m0, s51
	s_nop 0
	global_load_lds_dwordx4 v[194:195], off
	s_setprio 1
	s_barrier
	s_waitcnt lgkmcnt(0)
	v_mfma_f32_16x16x32_bf16 v[94:97], v[210:213], v[166:169], v[94:97]
	v_mfma_f32_16x16x32_bf16 v[90:93], v[218:221], v[166:169], v[90:93]
	v_mfma_f32_16x16x32_bf16 v[86:89], v[210:213], v[174:177], v[86:89]
	v_mfma_f32_16x16x32_bf16 v[82:85], v[218:221], v[174:177], v[82:85]
	v_mfma_f32_16x16x32_bf16 v[78:81], v[210:213], v[182:185], v[78:81]
	v_mfma_f32_16x16x32_bf16 v[74:77], v[218:221], v[182:185], v[74:77]
	v_mfma_f32_16x16x32_bf16 v[70:73], v[210:213], v[202:205], v[70:73]
	v_mfma_f32_16x16x32_bf16 v[66:69], v[218:221], v[202:205], v[66:69]
	v_mfma_f32_16x16x32_bf16 v[94:97], v[214:217], v[170:173], v[94:97]
	v_mfma_f32_16x16x32_bf16 v[90:93], v[242:245], v[170:173], v[90:93]
	v_mfma_f32_16x16x32_bf16 v[86:89], v[214:217], v[178:181], v[86:89]
	v_mfma_f32_16x16x32_bf16 v[82:85], v[242:245], v[178:181], v[82:85]
	v_mfma_f32_16x16x32_bf16 v[78:81], v[214:217], v[186:189], v[78:81]
	v_mfma_f32_16x16x32_bf16 v[74:77], v[242:245], v[186:189], v[74:77]
	v_mfma_f32_16x16x32_bf16 v[70:73], v[214:217], v[206:209], v[70:73]
	v_mfma_f32_16x16x32_bf16 v[66:69], v[242:245], v[206:209], v[66:69]
	s_setprio 0
	s_mov_b32 m0, s52
	v_lshl_add_u64 v[196:197], s[34:35], 0, v[0:1]
	s_barrier
	ds_read_b128 v[166:169], v137 offset:16384
	ds_read_b128 v[170:173], v137 offset:17408
	ds_read_b128 v[174:177], v137 offset:18432
	ds_read_b128 v[178:181], v137 offset:19456
	ds_read_b128 v[182:185], v137 offset:20480
	ds_read_b128 v[186:189], v137 offset:21504
	ds_read_b128 v[202:205], v137 offset:22528
	ds_read_b128 v[206:209], v137 offset:23552
	global_load_lds_dwordx4 v[196:197], off
	v_lshl_add_u64 v[222:223], s[34:35], 0, v[130:131]
	s_mov_b32 m0, s53
	s_nop 0
	global_load_lds_dwordx4 v[222:223], off
	s_setprio 1
	s_barrier
	s_waitcnt lgkmcnt(0)
	v_mfma_f32_16x16x32_bf16 v[62:65], v[138:141], v[166:169], v[62:65]
	v_mfma_f32_16x16x32_bf16 v[58:61], v[148:151], v[166:169], v[58:61]
	v_mfma_f32_16x16x32_bf16 v[54:57], v[138:141], v[174:177], v[54:57]
	v_mfma_f32_16x16x32_bf16 v[50:53], v[148:151], v[174:177], v[50:53]
	v_mfma_f32_16x16x32_bf16 v[46:49], v[138:141], v[182:185], v[46:49]
	v_mfma_f32_16x16x32_bf16 v[42:45], v[148:151], v[182:185], v[42:45]
	v_mfma_f32_16x16x32_bf16 v[38:41], v[138:141], v[202:205], v[38:41]
	v_mfma_f32_16x16x32_bf16 v[34:37], v[148:151], v[202:205], v[34:37]
	v_mfma_f32_16x16x32_bf16 v[62:65], v[142:145], v[170:173], v[62:65]
	v_mfma_f32_16x16x32_bf16 v[58:61], v[162:165], v[170:173], v[58:61]
	v_mfma_f32_16x16x32_bf16 v[54:57], v[142:145], v[178:181], v[54:57]
	v_mfma_f32_16x16x32_bf16 v[50:53], v[162:165], v[178:181], v[50:53]
	v_mfma_f32_16x16x32_bf16 v[46:49], v[142:145], v[186:189], v[46:49]
	v_mfma_f32_16x16x32_bf16 v[42:45], v[162:165], v[186:189], v[42:45]
	v_mfma_f32_16x16x32_bf16 v[38:41], v[142:145], v[206:209], v[38:41]
	v_mfma_f32_16x16x32_bf16 v[34:37], v[162:165], v[206:209], v[34:37]
	s_setprio 0
	s_barrier
	s_add_u32 s0, s42, s49
	s_addc_u32 s1, s43, 0
	s_mov_b32 m0, s54
	v_lshl_add_u64 v[246:247], s[0:1], 0, v[0:1]
	global_load_lds_dwordx4 v[246:247], off
	v_lshl_add_u64 v[248:249], s[0:1], 0, v[130:131]
	s_mov_b32 m0, s55
	s_nop 0
	global_load_lds_dwordx4 v[248:249], off
	s_waitcnt vmcnt(6)
	s_setprio 1
	s_barrier
	v_mfma_f32_16x16x32_bf16 v[30:33], v[210:213], v[166:169], v[30:33]
	v_mfma_f32_16x16x32_bf16 v[26:29], v[218:221], v[166:169], v[26:29]
	v_mfma_f32_16x16x32_bf16 v[22:25], v[210:213], v[174:177], v[22:25]
	v_mfma_f32_16x16x32_bf16 v[18:21], v[218:221], v[174:177], v[18:21]
	v_mfma_f32_16x16x32_bf16 v[14:17], v[210:213], v[182:185], v[14:17]
	v_mfma_f32_16x16x32_bf16 v[10:13], v[218:221], v[182:185], v[10:13]
	v_mfma_f32_16x16x32_bf16 v[6:9], v[210:213], v[202:205], v[6:9]
	v_mfma_f32_16x16x32_bf16 v[2:5], v[218:221], v[202:205], v[2:5]
	v_mfma_f32_16x16x32_bf16 v[30:33], v[214:217], v[170:173], v[30:33]
	v_mfma_f32_16x16x32_bf16 v[26:29], v[242:245], v[170:173], v[26:29]
	v_mfma_f32_16x16x32_bf16 v[22:25], v[214:217], v[178:181], v[22:25]
	v_mfma_f32_16x16x32_bf16 v[18:21], v[242:245], v[178:181], v[18:21]
	v_mfma_f32_16x16x32_bf16 v[14:17], v[214:217], v[186:189], v[14:17]
	v_mfma_f32_16x16x32_bf16 v[10:13], v[242:245], v[186:189], v[10:13]
	v_mfma_f32_16x16x32_bf16 v[6:9], v[214:217], v[206:209], v[6:9]
	v_mfma_f32_16x16x32_bf16 v[2:5], v[242:245], v[206:209], v[2:5]
	s_setprio 0
	v_add_u32_e32 v162, s25, v136
	s_barrier
	ds_read_b128 v[138:141], v162
	ds_read_b128 v[142:145], v162 offset:1024
	ds_read_b128 v[148:151], v162 offset:2048
	ds_read_b128 v[162:165], v162 offset:3072
	s_add_u32 s0, s34, s49
	s_addc_u32 s1, s35, 0
	s_mov_b32 m0, s58
	v_lshl_add_u64 v[210:211], s[0:1], 0, v[0:1]
	ds_read_b128 v[166:169], v137 offset:32768
	ds_read_b128 v[170:173], v137 offset:33792
	ds_read_b128 v[174:177], v137 offset:34816
	ds_read_b128 v[178:181], v137 offset:35840
	ds_read_b128 v[182:185], v137 offset:36864
	ds_read_b128 v[186:189], v137 offset:37888
	ds_read_b128 v[202:205], v137 offset:38912
	ds_read_b128 v[206:209], v137 offset:39936
	global_load_lds_dwordx4 v[210:211], off
	v_lshl_add_u64 v[210:211], s[0:1], 0, v[130:131]
	s_mov_b32 m0, s60
	s_nop 0
	global_load_lds_dwordx4 v[210:211], off
	s_waitcnt lgkmcnt(8)
	s_setprio 1
	s_barrier
	s_waitcnt lgkmcnt(0)
	v_mfma_f32_16x16x32_bf16 v[126:129], v[138:141], v[166:169], v[126:129]
	v_mfma_f32_16x16x32_bf16 v[122:125], v[148:151], v[166:169], v[122:125]
	v_mfma_f32_16x16x32_bf16 v[118:121], v[138:141], v[174:177], v[118:121]
	v_mfma_f32_16x16x32_bf16 v[114:117], v[148:151], v[174:177], v[114:117]
	v_mfma_f32_16x16x32_bf16 v[110:113], v[138:141], v[182:185], v[110:113]
	v_mfma_f32_16x16x32_bf16 v[106:109], v[148:151], v[182:185], v[106:109]
	v_mfma_f32_16x16x32_bf16 v[102:105], v[138:141], v[202:205], v[102:105]
	v_mfma_f32_16x16x32_bf16 v[98:101], v[148:151], v[202:205], v[98:101]
	v_mfma_f32_16x16x32_bf16 v[126:129], v[142:145], v[170:173], v[126:129]
	v_mfma_f32_16x16x32_bf16 v[122:125], v[162:165], v[170:173], v[122:125]
	v_mfma_f32_16x16x32_bf16 v[118:121], v[142:145], v[178:181], v[118:121]
	v_mfma_f32_16x16x32_bf16 v[114:117], v[162:165], v[178:181], v[114:117]
	v_mfma_f32_16x16x32_bf16 v[110:113], v[142:145], v[186:189], v[110:113]
	v_mfma_f32_16x16x32_bf16 v[106:109], v[162:165], v[186:189], v[106:109]
	v_mfma_f32_16x16x32_bf16 v[102:105], v[142:145], v[206:209], v[102:105]
	v_mfma_f32_16x16x32_bf16 v[98:101], v[162:165], v[206:209], v[98:101]
	s_setprio 0
	s_barrier
	s_mov_b32 m0, s61
	v_add_u32_e32 v201, s26, v136
	v_lshl_add_u64 v[152:153], v[152:153], 0, s[88:89]
	ds_read_b128 v[210:213], v201
	ds_read_b128 v[214:217], v201 offset:1024
	ds_read_b128 v[218:221], v201 offset:2048
	ds_read_b128 v[242:245], v201 offset:3072
	global_load_lds_dwordx4 v[152:153], off
	v_lshl_add_u64 v[152:153], v[194:195], 0, s[88:89]
	s_mov_b32 m0, s62
	s_nop 0
	global_load_lds_dwordx4 v[152:153], off
	s_setprio 1
	s_barrier
	s_waitcnt lgkmcnt(0)
	v_mfma_f32_16x16x32_bf16 v[94:97], v[210:213], v[166:169], v[94:97]
	v_mfma_f32_16x16x32_bf16 v[90:93], v[218:221], v[166:169], v[90:93]
	v_mfma_f32_16x16x32_bf16 v[86:89], v[210:213], v[174:177], v[86:89]
	v_mfma_f32_16x16x32_bf16 v[82:85], v[218:221], v[174:177], v[82:85]
	v_mfma_f32_16x16x32_bf16 v[78:81], v[210:213], v[182:185], v[78:81]
	v_mfma_f32_16x16x32_bf16 v[74:77], v[218:221], v[182:185], v[74:77]
	v_mfma_f32_16x16x32_bf16 v[70:73], v[210:213], v[202:205], v[70:73]
	v_mfma_f32_16x16x32_bf16 v[66:69], v[218:221], v[202:205], v[66:69]
	v_mfma_f32_16x16x32_bf16 v[94:97], v[214:217], v[170:173], v[94:97]
	v_mfma_f32_16x16x32_bf16 v[90:93], v[242:245], v[170:173], v[90:93]
	v_mfma_f32_16x16x32_bf16 v[86:89], v[214:217], v[178:181], v[86:89]
	v_mfma_f32_16x16x32_bf16 v[82:85], v[242:245], v[178:181], v[82:85]
	v_mfma_f32_16x16x32_bf16 v[78:81], v[214:217], v[186:189], v[78:81]
	v_mfma_f32_16x16x32_bf16 v[74:77], v[242:245], v[186:189], v[74:77]
	v_mfma_f32_16x16x32_bf16 v[70:73], v[214:217], v[206:209], v[70:73]
	v_mfma_f32_16x16x32_bf16 v[66:69], v[242:245], v[206:209], v[66:69]
	s_setprio 0
	s_mov_b32 m0, s63
	v_lshl_add_u64 v[152:153], v[196:197], 0, s[88:89]
	s_barrier
	ds_read_b128 v[166:169], v137 offset:49152
	ds_read_b128 v[170:173], v137 offset:50176
	ds_read_b128 v[174:177], v137 offset:51200
	ds_read_b128 v[178:181], v137 offset:52224
	ds_read_b128 v[182:185], v137 offset:53248
	ds_read_b128 v[186:189], v137 offset:54272
	ds_read_b128 v[202:205], v137 offset:55296
	ds_read_b128 v[206:209], v137 offset:56320
	global_load_lds_dwordx4 v[152:153], off
	v_lshl_add_u64 v[152:153], v[222:223], 0, s[88:89]
	s_mov_b32 m0, s66
	s_nop 0
	global_load_lds_dwordx4 v[152:153], off
	s_setprio 1
	s_barrier
	s_waitcnt lgkmcnt(0)
	v_mfma_f32_16x16x32_bf16 v[62:65], v[138:141], v[166:169], v[62:65]
	v_mfma_f32_16x16x32_bf16 v[58:61], v[148:151], v[166:169], v[58:61]
	v_mfma_f32_16x16x32_bf16 v[54:57], v[138:141], v[174:177], v[54:57]
	v_mfma_f32_16x16x32_bf16 v[50:53], v[148:151], v[174:177], v[50:53]
	v_mfma_f32_16x16x32_bf16 v[46:49], v[138:141], v[182:185], v[46:49]
	v_mfma_f32_16x16x32_bf16 v[42:45], v[148:151], v[182:185], v[42:45]
	v_mfma_f32_16x16x32_bf16 v[38:41], v[138:141], v[202:205], v[38:41]
	v_mfma_f32_16x16x32_bf16 v[34:37], v[148:151], v[202:205], v[34:37]
	v_mfma_f32_16x16x32_bf16 v[62:65], v[142:145], v[170:173], v[62:65]
	v_mfma_f32_16x16x32_bf16 v[58:61], v[162:165], v[170:173], v[58:61]
	v_mfma_f32_16x16x32_bf16 v[54:57], v[142:145], v[178:181], v[54:57]
	v_mfma_f32_16x16x32_bf16 v[50:53], v[162:165], v[178:181], v[50:53]
	v_mfma_f32_16x16x32_bf16 v[46:49], v[142:145], v[186:189], v[46:49]
	v_mfma_f32_16x16x32_bf16 v[42:45], v[162:165], v[186:189], v[42:45]
	v_mfma_f32_16x16x32_bf16 v[38:41], v[142:145], v[206:209], v[38:41]
	v_mfma_f32_16x16x32_bf16 v[34:37], v[162:165], v[206:209], v[34:37]
	s_setprio 0
	s_barrier
	s_mov_b32 m0, s67
	v_lshl_add_u64 v[138:139], v[246:247], 0, s[88:89]
	global_load_lds_dwordx4 v[138:139], off
	v_lshl_add_u64 v[138:139], v[248:249], 0, s[88:89]
	s_mov_b32 m0, s68
	s_nop 0
	global_load_lds_dwordx4 v[138:139], off
	s_waitcnt vmcnt(6)
	s_setprio 1
	s_barrier
	v_mfma_f32_16x16x32_bf16 v[30:33], v[210:213], v[166:169], v[30:33]
	v_mfma_f32_16x16x32_bf16 v[26:29], v[218:221], v[166:169], v[26:29]
	v_mfma_f32_16x16x32_bf16 v[22:25], v[210:213], v[174:177], v[22:25]
	v_mfma_f32_16x16x32_bf16 v[18:21], v[218:221], v[174:177], v[18:21]
	v_mfma_f32_16x16x32_bf16 v[14:17], v[210:213], v[182:185], v[14:17]
	v_mfma_f32_16x16x32_bf16 v[10:13], v[218:221], v[182:185], v[10:13]
	v_mfma_f32_16x16x32_bf16 v[6:9], v[210:213], v[202:205], v[6:9]
	v_mfma_f32_16x16x32_bf16 v[2:5], v[218:221], v[202:205], v[2:5]
	v_mfma_f32_16x16x32_bf16 v[30:33], v[214:217], v[170:173], v[30:33]
	v_mfma_f32_16x16x32_bf16 v[26:29], v[242:245], v[170:173], v[26:29]
	v_mfma_f32_16x16x32_bf16 v[22:25], v[214:217], v[178:181], v[22:25]
	v_mfma_f32_16x16x32_bf16 v[18:21], v[242:245], v[178:181], v[18:21]
	v_mfma_f32_16x16x32_bf16 v[14:17], v[214:217], v[186:189], v[14:17]
	v_mfma_f32_16x16x32_bf16 v[10:13], v[242:245], v[186:189], v[10:13]
	v_mfma_f32_16x16x32_bf16 v[6:9], v[214:217], v[206:209], v[6:9]
	v_mfma_f32_16x16x32_bf16 v[2:5], v[242:245], v[206:209], v[2:5]
	s_setprio 0
	s_add_u32 s20, s20, 0x100
	s_addc_u32 s21, s21, 0
	s_cmp_ge_u32 s70, s44
	s_barrier
	s_cbranch_scc0 .LBB0_814
	v_readfirstlane_b32 s98, v191
	s_cmpk_gt_u32 s98, 0xff
	s_cbranch_scc1 .Lrl_e0_814
	s_barrier

.LBB0_1241:
	v_add_u32_e32 v0, s37, v144
	ds_read_b128 v[140:143], v0
	ds_read_b128 v[150:153], v0 offset:1024
	ds_read_b128 v[154:157], v0 offset:2048
	ds_read_b128 v[158:161], v0 offset:3072
	s_add_u32 s0, s20, 0xfffc0080
	s_addc_u32 s1, s21, -1
	s_cmp_eq_u32 s51, 12
	s_cselect_b32 s49, s15, s1
	s_cselect_b32 s48, s29, s0
	s_cselect_b32 s35, s7, s50
	s_cselect_b32 s34, s43, s45
	v_lshl_add_u64 v[194:195], s[20:21], 0, v[136:137]
	s_add_i32 m0, s66, 0xc000
	ds_read_b128 v[162:165], v149
	ds_read_b128 v[166:169], v149 offset:1024
	ds_read_b128 v[170:173], v149 offset:2048
	ds_read_b128 v[174:177], v149 offset:3072
	ds_read_b128 v[178:181], v149 offset:4096
	ds_read_b128 v[182:185], v149 offset:5120
	ds_read_b128 v[186:189], v149 offset:6144
	ds_read_b128 v[202:205], v149 offset:7168
	global_load_lds_dwordx4 v[194:195], off
	v_lshl_add_u64 v[194:195], s[20:21], 0, v[138:139]
	s_add_i32 m0, s66, 0xe000
	s_nop 0
	global_load_lds_dwordx4 v[194:195], off
	s_waitcnt lgkmcnt(8)
	s_setprio 1
	s_barrier
	s_waitcnt lgkmcnt(0)
	v_mfma_f32_16x16x32_bf16 v[126:129], v[140:143], v[162:165], v[126:129]
	v_mfma_f32_16x16x32_bf16 v[122:125], v[154:157], v[162:165], v[122:125]
	v_mfma_f32_16x16x32_bf16 v[110:113], v[140:143], v[170:173], v[110:113]
	v_mfma_f32_16x16x32_bf16 v[106:109], v[154:157], v[170:173], v[106:109]
	v_mfma_f32_16x16x32_bf16 v[94:97], v[140:143], v[178:181], v[94:97]
	v_mfma_f32_16x16x32_bf16 v[90:93], v[154:157], v[178:181], v[90:93]
	v_mfma_f32_16x16x32_bf16 v[78:81], v[140:143], v[186:189], v[78:81]
	v_mfma_f32_16x16x32_bf16 v[74:77], v[154:157], v[186:189], v[74:77]
	v_mfma_f32_16x16x32_bf16 v[126:129], v[150:153], v[166:169], v[126:129]
	v_mfma_f32_16x16x32_bf16 v[122:125], v[158:161], v[166:169], v[122:125]
	v_mfma_f32_16x16x32_bf16 v[110:113], v[150:153], v[174:177], v[110:113]
	v_mfma_f32_16x16x32_bf16 v[106:109], v[158:161], v[174:177], v[106:109]
	v_mfma_f32_16x16x32_bf16 v[94:97], v[150:153], v[182:185], v[94:97]
	v_mfma_f32_16x16x32_bf16 v[90:93], v[158:161], v[182:185], v[90:93]
	v_mfma_f32_16x16x32_bf16 v[78:81], v[150:153], v[202:205], v[78:81]
	v_mfma_f32_16x16x32_bf16 v[74:77], v[158:161], v[202:205], v[74:77]
	s_setprio 0
	s_barrier
	s_mov_b32 m0, s62
	v_add_u32_e32 v0, s26, v144
	v_lshl_add_u64 v[194:195], s[34:35], 0, v[130:131]
	ds_read_b128 v[206:209], v0
	ds_read_b128 v[210:213], v0 offset:1024
	ds_read_b128 v[214:217], v0 offset:2048
	ds_read_b128 v[218:221], v0 offset:3072
	global_load_lds_dwordx4 v[194:195], off
	v_lshl_add_u64 v[196:197], s[34:35], 0, v[132:133]
	s_mov_b32 m0, s63
	s_nop 0
	global_load_lds_dwordx4 v[196:197], off
	s_setprio 1
	s_barrier
	s_waitcnt lgkmcnt(0)
	v_mfma_f32_16x16x32_bf16 v[118:121], v[206:209], v[162:165], v[118:121]
	v_mfma_f32_16x16x32_bf16 v[114:117], v[214:217], v[162:165], v[114:117]
	v_mfma_f32_16x16x32_bf16 v[102:105], v[206:209], v[170:173], v[102:105]
	v_mfma_f32_16x16x32_bf16 v[98:101], v[214:217], v[170:173], v[98:101]
	v_mfma_f32_16x16x32_bf16 v[86:89], v[206:209], v[178:181], v[86:89]
	v_mfma_f32_16x16x32_bf16 v[82:85], v[214:217], v[178:181], v[82:85]
	v_mfma_f32_16x16x32_bf16 v[70:73], v[206:209], v[186:189], v[70:73]
	v_mfma_f32_16x16x32_bf16 v[66:69], v[214:217], v[186:189], v[66:69]
	v_mfma_f32_16x16x32_bf16 v[118:121], v[210:213], v[166:169], v[118:121]
	v_mfma_f32_16x16x32_bf16 v[114:117], v[218:221], v[166:169], v[114:117]
	v_mfma_f32_16x16x32_bf16 v[102:105], v[210:213], v[174:177], v[102:105]
	v_mfma_f32_16x16x32_bf16 v[98:101], v[218:221], v[174:177], v[98:101]
	v_mfma_f32_16x16x32_bf16 v[86:89], v[210:213], v[182:185], v[86:89]
	v_mfma_f32_16x16x32_bf16 v[82:85], v[218:221], v[182:185], v[82:85]
	v_mfma_f32_16x16x32_bf16 v[70:73], v[210:213], v[202:205], v[70:73]
	v_mfma_f32_16x16x32_bf16 v[66:69], v[218:221], v[202:205], v[66:69]
	s_setprio 0
	s_mov_b32 m0, s66
	v_lshl_add_u64 v[222:223], s[48:49], 0, v[130:131]
	s_barrier
	ds_read_b128 v[162:165], v149 offset:16384
	ds_read_b128 v[166:169], v149 offset:17408
	ds_read_b128 v[170:173], v149 offset:18432
	ds_read_b128 v[174:177], v149 offset:19456
	ds_read_b128 v[178:181], v149 offset:20480
	ds_read_b128 v[182:185], v149 offset:21504
	ds_read_b128 v[186:189], v149 offset:22528
	ds_read_b128 v[202:205], v149 offset:23552
	global_load_lds_dwordx4 v[222:223], off
	v_lshl_add_u64 v[242:243], s[48:49], 0, v[132:133]
	s_mov_b32 m0, s67
	s_nop 0
	global_load_lds_dwordx4 v[242:243], off
	s_setprio 1
	s_barrier
	s_waitcnt lgkmcnt(0)
	v_mfma_f32_16x16x32_bf16 v[62:65], v[140:143], v[162:165], v[62:65]
	v_mfma_f32_16x16x32_bf16 v[58:61], v[154:157], v[162:165], v[58:61]
	v_mfma_f32_16x16x32_bf16 v[46:49], v[140:143], v[170:173], v[46:49]
	v_mfma_f32_16x16x32_bf16 v[42:45], v[154:157], v[170:173], v[42:45]
	v_mfma_f32_16x16x32_bf16 v[30:33], v[140:143], v[178:181], v[30:33]
	v_mfma_f32_16x16x32_bf16 v[26:29], v[154:157], v[178:181], v[26:29]
	v_mfma_f32_16x16x32_bf16 v[14:17], v[140:143], v[186:189], v[14:17]
	v_mfma_f32_16x16x32_bf16 v[10:13], v[154:157], v[186:189], v[10:13]
	v_mfma_f32_16x16x32_bf16 v[62:65], v[150:153], v[166:169], v[62:65]
	v_mfma_f32_16x16x32_bf16 v[58:61], v[158:161], v[166:169], v[58:61]
	v_mfma_f32_16x16x32_bf16 v[46:49], v[150:153], v[174:177], v[46:49]
	v_mfma_f32_16x16x32_bf16 v[42:45], v[158:161], v[174:177], v[42:45]
	v_mfma_f32_16x16x32_bf16 v[30:33], v[150:153], v[182:185], v[30:33]
	v_mfma_f32_16x16x32_bf16 v[26:29], v[158:161], v[182:185], v[26:29]
	v_mfma_f32_16x16x32_bf16 v[14:17], v[150:153], v[202:205], v[14:17]
	v_mfma_f32_16x16x32_bf16 v[10:13], v[158:161], v[202:205], v[10:13]
	s_setprio 0
	s_barrier
	s_add_u32 s0, s34, 0x40000
	s_addc_u32 s1, s35, 0
	s_mov_b32 m0, s68
	v_lshl_add_u64 v[140:141], s[0:1], 0, v[130:131]
	global_load_lds_dwordx4 v[140:141], off
	v_lshl_add_u64 v[140:141], s[0:1], 0, v[132:133]
	s_mov_b32 m0, s28
	s_nop 0
	global_load_lds_dwordx4 v[140:141], off
	s_waitcnt vmcnt(6)
	s_setprio 1
	s_barrier
	v_mfma_f32_16x16x32_bf16 v[54:57], v[206:209], v[162:165], v[54:57]
	v_mfma_f32_16x16x32_bf16 v[50:53], v[214:217], v[162:165], v[50:53]
	v_mfma_f32_16x16x32_bf16 v[38:41], v[206:209], v[170:173], v[38:41]
	v_mfma_f32_16x16x32_bf16 v[34:37], v[214:217], v[170:173], v[34:37]
	v_mfma_f32_16x16x32_bf16 v[22:25], v[206:209], v[178:181], v[22:25]
	v_mfma_f32_16x16x32_bf16 v[18:21], v[214:217], v[178:181], v[18:21]
	v_mfma_f32_16x16x32_bf16 v[6:9], v[206:209], v[186:189], v[6:9]
	v_mfma_f32_16x16x32_bf16 v[2:5], v[214:217], v[186:189], v[2:5]
	v_mfma_f32_16x16x32_bf16 v[54:57], v[210:213], v[166:169], v[54:57]
	v_mfma_f32_16x16x32_bf16 v[50:53], v[218:221], v[166:169], v[50:53]
	v_mfma_f32_16x16x32_bf16 v[38:41], v[210:213], v[174:177], v[38:41]
	v_mfma_f32_16x16x32_bf16 v[34:37], v[218:221], v[174:177], v[34:37]
	v_mfma_f32_16x16x32_bf16 v[22:25], v[210:213], v[182:185], v[22:25]
	v_mfma_f32_16x16x32_bf16 v[18:21], v[218:221], v[182:185], v[18:21]
	v_mfma_f32_16x16x32_bf16 v[6:9], v[210:213], v[202:205], v[6:9]
	v_mfma_f32_16x16x32_bf16 v[2:5], v[218:221], v[202:205], v[2:5]
	s_setprio 0
	v_add_u32_e32 v0, s36, v144
	s_barrier
	ds_read_b128 v[140:143], v0
	ds_read_b128 v[150:153], v0 offset:1024
	ds_read_b128 v[154:157], v0 offset:2048
	ds_read_b128 v[158:161], v0 offset:3072
	s_add_u32 s0, s48, 0x40000
	s_addc_u32 s1, s49, 0
	s_mov_b32 m0, s30
	v_lshl_add_u64 v[206:207], s[0:1], 0, v[130:131]
	ds_read_b128 v[162:165], v149 offset:32768
	ds_read_b128 v[166:169], v149 offset:33792
	ds_read_b128 v[170:173], v149 offset:34816
	ds_read_b128 v[174:177], v149 offset:35840
	ds_read_b128 v[178:181], v149 offset:36864
	ds_read_b128 v[182:185], v149 offset:37888
	ds_read_b128 v[186:189], v149 offset:38912
	ds_read_b128 v[202:205], v149 offset:39936
	global_load_lds_dwordx4 v[206:207], off
	v_lshl_add_u64 v[206:207], s[0:1], 0, v[132:133]
	s_mov_b32 m0, s69
	s_nop 0
	global_load_lds_dwordx4 v[206:207], off
	s_waitcnt lgkmcnt(8)
	s_setprio 1
	s_barrier
	s_waitcnt lgkmcnt(0)
	v_mfma_f32_16x16x32_bf16 v[126:129], v[140:143], v[162:165], v[126:129]
	v_mfma_f32_16x16x32_bf16 v[122:125], v[154:157], v[162:165], v[122:125]
	v_mfma_f32_16x16x32_bf16 v[110:113], v[140:143], v[170:173], v[110:113]
	v_mfma_f32_16x16x32_bf16 v[106:109], v[154:157], v[170:173], v[106:109]
	v_mfma_f32_16x16x32_bf16 v[94:97], v[140:143], v[178:181], v[94:97]
	v_mfma_f32_16x16x32_bf16 v[90:93], v[154:157], v[178:181], v[90:93]
	v_mfma_f32_16x16x32_bf16 v[78:81], v[140:143], v[186:189], v[78:81]
	v_mfma_f32_16x16x32_bf16 v[74:77], v[154:157], v[186:189], v[74:77]
	v_mfma_f32_16x16x32_bf16 v[126:129], v[150:153], v[166:169], v[126:129]
	v_mfma_f32_16x16x32_bf16 v[122:125], v[158:161], v[166:169], v[122:125]
	v_mfma_f32_16x16x32_bf16 v[110:113], v[150:153], v[174:177], v[110:113]
	v_mfma_f32_16x16x32_bf16 v[106:109], v[158:161], v[174:177], v[106:109]
	v_mfma_f32_16x16x32_bf16 v[94:97], v[150:153], v[182:185], v[94:97]
	v_mfma_f32_16x16x32_bf16 v[90:93], v[158:161], v[182:185], v[90:93]
	v_mfma_f32_16x16x32_bf16 v[78:81], v[150:153], v[202:205], v[78:81]
	v_mfma_f32_16x16x32_bf16 v[74:77], v[158:161], v[202:205], v[74:77]
	s_setprio 0
	s_barrier
	s_mov_b32 m0, s38
	v_add_u32_e32 v0, s8, v144
	v_lshl_add_u64 v[194:195], v[194:195], 0, s[88:89]
	ds_read_b128 v[206:209], v0
	ds_read_b128 v[210:213], v0 offset:1024
	ds_read_b128 v[214:217], v0 offset:2048
	ds_read_b128 v[218:221], v0 offset:3072
	global_load_lds_dwordx4 v[194:195], off
	v_lshl_add_u64 v[194:195], v[196:197], 0, s[88:89]
	s_mov_b32 m0, s58
	s_nop 0
	global_load_lds_dwordx4 v[194:195], off
	s_setprio 1
	s_barrier
	s_waitcnt lgkmcnt(0)
	v_mfma_f32_16x16x32_bf16 v[118:121], v[206:209], v[162:165], v[118:121]
	v_mfma_f32_16x16x32_bf16 v[114:117], v[214:217], v[162:165], v[114:117]
	v_mfma_f32_16x16x32_bf16 v[102:105], v[206:209], v[170:173], v[102:105]
	v_mfma_f32_16x16x32_bf16 v[98:101], v[214:217], v[170:173], v[98:101]
	v_mfma_f32_16x16x32_bf16 v[86:89], v[206:209], v[178:181], v[86:89]
	v_mfma_f32_16x16x32_bf16 v[82:85], v[214:217], v[178:181], v[82:85]
	v_mfma_f32_16x16x32_bf16 v[70:73], v[206:209], v[186:189], v[70:73]
	v_mfma_f32_16x16x32_bf16 v[66:69], v[214:217], v[186:189], v[66:69]
	v_mfma_f32_16x16x32_bf16 v[118:121], v[210:213], v[166:169], v[118:121]
	v_mfma_f32_16x16x32_bf16 v[114:117], v[218:221], v[166:169], v[114:117]
	v_mfma_f32_16x16x32_bf16 v[102:105], v[210:213], v[174:177], v[102:105]
	v_mfma_f32_16x16x32_bf16 v[98:101], v[218:221], v[174:177], v[98:101]
	v_mfma_f32_16x16x32_bf16 v[86:89], v[210:213], v[182:185], v[86:89]
	v_mfma_f32_16x16x32_bf16 v[82:85], v[218:221], v[182:185], v[82:85]
	v_mfma_f32_16x16x32_bf16 v[70:73], v[210:213], v[202:205], v[70:73]
	v_mfma_f32_16x16x32_bf16 v[66:69], v[218:221], v[202:205], v[66:69]
	s_setprio 0
	s_mov_b32 m0, s76
	v_lshl_add_u64 v[194:195], v[222:223], 0, s[88:89]
	s_barrier
	ds_read_b128 v[162:165], v149 offset:49152
	ds_read_b128 v[166:169], v149 offset:50176
	ds_read_b128 v[170:173], v149 offset:51200
	ds_read_b128 v[174:177], v149 offset:52224
	ds_read_b128 v[178:181], v149 offset:53248
	ds_read_b128 v[182:185], v149 offset:54272
	ds_read_b128 v[186:189], v149 offset:55296
	ds_read_b128 v[202:205], v149 offset:56320
	global_load_lds_dwordx4 v[194:195], off
	v_lshl_add_u64 v[194:195], v[242:243], 0, s[88:89]
	s_mov_b32 m0, s4
	s_nop 0
	global_load_lds_dwordx4 v[194:195], off
	s_setprio 1
	s_barrier
	s_waitcnt lgkmcnt(0)
	v_mfma_f32_16x16x32_bf16 v[62:65], v[140:143], v[162:165], v[62:65]
	v_mfma_f32_16x16x32_bf16 v[58:61], v[154:157], v[162:165], v[58:61]
	v_mfma_f32_16x16x32_bf16 v[46:49], v[140:143], v[170:173], v[46:49]
	v_mfma_f32_16x16x32_bf16 v[42:45], v[154:157], v[170:173], v[42:45]
	v_mfma_f32_16x16x32_bf16 v[30:33], v[140:143], v[178:181], v[30:33]
	v_mfma_f32_16x16x32_bf16 v[26:29], v[154:157], v[178:181], v[26:29]
	v_mfma_f32_16x16x32_bf16 v[14:17], v[140:143], v[186:189], v[14:17]
	v_mfma_f32_16x16x32_bf16 v[10:13], v[154:157], v[186:189], v[10:13]
	v_mfma_f32_16x16x32_bf16 v[62:65], v[150:153], v[166:169], v[62:65]
	v_mfma_f32_16x16x32_bf16 v[58:61], v[158:161], v[166:169], v[58:61]
	v_mfma_f32_16x16x32_bf16 v[46:49], v[150:153], v[174:177], v[46:49]
	v_mfma_f32_16x16x32_bf16 v[42:45], v[158:161], v[174:177], v[42:45]
	v_mfma_f32_16x16x32_bf16 v[30:33], v[150:153], v[182:185], v[30:33]
	v_mfma_f32_16x16x32_bf16 v[26:29], v[158:161], v[182:185], v[26:29]
	v_mfma_f32_16x16x32_bf16 v[14:17], v[150:153], v[202:205], v[14:17]
	v_mfma_f32_16x16x32_bf16 v[10:13], v[158:161], v[202:205], v[10:13]
	s_setprio 0
	s_barrier
	s_add_u32 s0, s34, 0x40080
	s_addc_u32 s1, s35, 0
	s_mov_b32 m0, s10
	v_lshl_add_u64 v[140:141], s[0:1], 0, v[130:131]
	global_load_lds_dwordx4 v[140:141], off
	v_lshl_add_u64 v[140:141], s[0:1], 0, v[132:133]
	s_mov_b32 m0, s11
	s_nop 0
	global_load_lds_dwordx4 v[140:141], off
	s_waitcnt vmcnt(6)
	s_setprio 1
	s_barrier
	v_mfma_f32_16x16x32_bf16 v[54:57], v[206:209], v[162:165], v[54:57]
	v_mfma_f32_16x16x32_bf16 v[50:53], v[214:217], v[162:165], v[50:53]
	v_mfma_f32_16x16x32_bf16 v[38:41], v[206:209], v[170:173], v[38:41]
	v_mfma_f32_16x16x32_bf16 v[34:37], v[214:217], v[170:173], v[34:37]
	v_mfma_f32_16x16x32_bf16 v[22:25], v[206:209], v[178:181], v[22:25]
	v_mfma_f32_16x16x32_bf16 v[18:21], v[214:217], v[178:181], v[18:21]
	v_mfma_f32_16x16x32_bf16 v[6:9], v[206:209], v[186:189], v[6:9]
	v_mfma_f32_16x16x32_bf16 v[2:5], v[214:217], v[186:189], v[2:5]
	v_mfma_f32_16x16x32_bf16 v[54:57], v[210:213], v[166:169], v[54:57]
	v_mfma_f32_16x16x32_bf16 v[50:53], v[218:221], v[166:169], v[50:53]
	v_mfma_f32_16x16x32_bf16 v[38:41], v[210:213], v[174:177], v[38:41]
	v_mfma_f32_16x16x32_bf16 v[34:37], v[218:221], v[174:177], v[34:37]
	v_mfma_f32_16x16x32_bf16 v[22:25], v[210:213], v[182:185], v[22:25]
	v_mfma_f32_16x16x32_bf16 v[18:21], v[218:221], v[182:185], v[18:21]
	v_mfma_f32_16x16x32_bf16 v[6:9], v[210:213], v[202:205], v[6:9]
	v_mfma_f32_16x16x32_bf16 v[2:5], v[218:221], v[202:205], v[2:5]
	s_setprio 0
	s_add_i32 s51, s51, 2
	s_add_u32 s20, s20, 0x100
	s_addc_u32 s21, s21, 0
	s_add_u32 s45, s45, 0x100
	s_addc_u32 s50, s50, 0
	s_cmp_gt_u32 s51, 13
	s_barrier
	s_cbranch_scc0 .LBB0_1241
	v_readfirstlane_b32 s98, v191
	s_cmpk_gt_u32 s98, 0xff
	s_cbranch_scc1 .Lrl_e0_1241
	s_barrier

.LBB0_1353:
	v_add_u32_e32 v0, s61, v187
	s_waitcnt vmcnt(0)
	ds_read_b128 v[130:133], v0
	ds_read_b128 v[134:137], v0 offset:1024
	ds_read_b128 v[138:141], v0 offset:2048
	ds_read_b128 v[142:145], v0 offset:3072
	s_add_u32 s0, s20, 0xfffc0080
	s_addc_u32 s1, s21, -1
	s_cmp_eq_u32 s26, 12
	s_cselect_b32 s43, s4, s1
	s_cselect_b32 s42, s8, s0
	s_cselect_b32 s35, s10, s25
	s_cselect_b32 s34, s11, s24
	v_lshl_add_u64 v[194:195], s[20:21], 0, v[174:175]
	s_add_i32 m0, s67, 0xc000
	ds_read_b128 v[146:149], v202
	ds_read_b128 v[150:153], v202 offset:1024
	ds_read_b128 v[154:157], v202 offset:2048
	ds_read_b128 v[158:161], v202 offset:3072
	ds_read_b128 v[178:181], v202 offset:4096
	ds_read_b128 v[182:185], v202 offset:5120
	ds_read_b128 v[204:207], v202 offset:6144
	ds_read_b128 v[208:211], v202 offset:7168
	global_load_lds_dwordx4 v[194:195], off
	v_lshl_add_u64 v[194:195], s[20:21], 0, v[176:177]
	s_add_i32 m0, s67, 0xe000
	s_nop 0
	global_load_lds_dwordx4 v[194:195], off
	s_waitcnt lgkmcnt(8)
	s_setprio 1
	s_barrier
	s_waitcnt lgkmcnt(0)
	v_mfma_f32_16x16x32_bf16 v[126:129], v[130:133], v[146:149], v[126:129]
	v_mfma_f32_16x16x32_bf16 v[122:125], v[138:141], v[146:149], v[122:125]
	v_mfma_f32_16x16x32_bf16 v[118:121], v[130:133], v[154:157], v[118:121]
	v_mfma_f32_16x16x32_bf16 v[114:117], v[138:141], v[154:157], v[114:117]
	v_mfma_f32_16x16x32_bf16 v[102:105], v[130:133], v[178:181], v[102:105]
	v_mfma_f32_16x16x32_bf16 v[98:101], v[138:141], v[178:181], v[98:101]
	v_mfma_f32_16x16x32_bf16 v[86:89], v[130:133], v[204:207], v[86:89]
	v_mfma_f32_16x16x32_bf16 v[82:85], v[138:141], v[204:207], v[82:85]
	v_mfma_f32_16x16x32_bf16 v[126:129], v[134:137], v[150:153], v[126:129]
	v_mfma_f32_16x16x32_bf16 v[122:125], v[142:145], v[150:153], v[122:125]
	v_mfma_f32_16x16x32_bf16 v[118:121], v[134:137], v[158:161], v[118:121]
	v_mfma_f32_16x16x32_bf16 v[114:117], v[142:145], v[158:161], v[114:117]
	v_mfma_f32_16x16x32_bf16 v[102:105], v[134:137], v[182:185], v[102:105]
	v_mfma_f32_16x16x32_bf16 v[98:101], v[142:145], v[182:185], v[98:101]
	v_mfma_f32_16x16x32_bf16 v[86:89], v[134:137], v[208:211], v[86:89]
	v_mfma_f32_16x16x32_bf16 v[82:85], v[142:145], v[208:211], v[82:85]
	s_setprio 0
	s_barrier
	s_mov_b32 m0, s62
	v_add_u32_e32 v0, s78, v187
	v_lshl_add_u64 v[194:195], s[34:35], 0, v[162:163]
	ds_read_b128 v[212:215], v0
	ds_read_b128 v[216:219], v0 offset:1024
	ds_read_b128 v[220:223], v0 offset:2048
	ds_read_b128 v[242:245], v0 offset:3072
	global_load_lds_dwordx4 v[194:195], off
	v_lshl_add_u64 v[196:197], s[34:35], 0, v[164:165]
	s_mov_b32 m0, s63
	s_nop 0
	global_load_lds_dwordx4 v[196:197], off
	s_setprio 1
	s_barrier
	s_waitcnt lgkmcnt(0)
	v_mfma_f32_16x16x32_bf16 v[110:113], v[212:215], v[146:149], v[110:113]
	v_mfma_f32_16x16x32_bf16 v[106:109], v[220:223], v[146:149], v[106:109]
	v_mfma_f32_16x16x32_bf16 v[94:97], v[212:215], v[154:157], v[94:97]
	v_mfma_f32_16x16x32_bf16 v[90:93], v[220:223], v[154:157], v[90:93]
	v_mfma_f32_16x16x32_bf16 v[78:81], v[212:215], v[178:181], v[78:81]
	v_mfma_f32_16x16x32_bf16 v[74:77], v[220:223], v[178:181], v[74:77]
	v_mfma_f32_16x16x32_bf16 v[70:73], v[212:215], v[204:207], v[70:73]
	v_mfma_f32_16x16x32_bf16 v[66:69], v[220:223], v[204:207], v[66:69]
	v_mfma_f32_16x16x32_bf16 v[110:113], v[216:219], v[150:153], v[110:113]
	v_mfma_f32_16x16x32_bf16 v[106:109], v[242:245], v[150:153], v[106:109]
	v_mfma_f32_16x16x32_bf16 v[94:97], v[216:219], v[158:161], v[94:97]
	v_mfma_f32_16x16x32_bf16 v[90:93], v[242:245], v[158:161], v[90:93]
	v_mfma_f32_16x16x32_bf16 v[78:81], v[216:219], v[182:185], v[78:81]
	v_mfma_f32_16x16x32_bf16 v[74:77], v[242:245], v[182:185], v[74:77]
	v_mfma_f32_16x16x32_bf16 v[70:73], v[216:219], v[208:211], v[70:73]
	v_mfma_f32_16x16x32_bf16 v[66:69], v[242:245], v[208:211], v[66:69]
	s_setprio 0
	s_mov_b32 m0, s67
	v_lshl_add_u64 v[246:247], s[42:43], 0, v[162:163]
	s_barrier
	ds_read_b128 v[146:149], v202 offset:16384
	ds_read_b128 v[150:153], v202 offset:17408
	ds_read_b128 v[154:157], v202 offset:18432
	ds_read_b128 v[158:161], v202 offset:19456
	ds_read_b128 v[178:181], v202 offset:20480
	ds_read_b128 v[182:185], v202 offset:21504
	ds_read_b128 v[204:207], v202 offset:22528
	ds_read_b128 v[208:211], v202 offset:23552
	global_load_lds_dwordx4 v[246:247], off
	v_lshl_add_u64 v[248:249], s[42:43], 0, v[164:165]
	s_mov_b32 m0, s75
	s_nop 0
	global_load_lds_dwordx4 v[248:249], off
	s_setprio 1
	s_barrier
	s_waitcnt lgkmcnt(0)
	v_mfma_f32_16x16x32_bf16 v[62:65], v[130:133], v[146:149], v[62:65]
	v_mfma_f32_16x16x32_bf16 v[58:61], v[138:141], v[146:149], v[58:61]
	v_mfma_f32_16x16x32_bf16 v[54:57], v[130:133], v[154:157], v[54:57]
	v_mfma_f32_16x16x32_bf16 v[50:53], v[138:141], v[154:157], v[50:53]
	v_mfma_f32_16x16x32_bf16 v[38:41], v[130:133], v[178:181], v[38:41]
	v_mfma_f32_16x16x32_bf16 v[34:37], v[138:141], v[178:181], v[34:37]
	v_mfma_f32_16x16x32_bf16 v[22:25], v[130:133], v[204:207], v[22:25]
	v_mfma_f32_16x16x32_bf16 v[14:17], v[138:141], v[204:207], v[14:17]
	v_mfma_f32_16x16x32_bf16 v[62:65], v[134:137], v[150:153], v[62:65]
	v_mfma_f32_16x16x32_bf16 v[58:61], v[142:145], v[150:153], v[58:61]
	v_mfma_f32_16x16x32_bf16 v[54:57], v[134:137], v[158:161], v[54:57]
	v_mfma_f32_16x16x32_bf16 v[50:53], v[142:145], v[158:161], v[50:53]
	v_mfma_f32_16x16x32_bf16 v[38:41], v[134:137], v[182:185], v[38:41]
	v_mfma_f32_16x16x32_bf16 v[34:37], v[142:145], v[182:185], v[34:37]
	v_mfma_f32_16x16x32_bf16 v[22:25], v[134:137], v[208:211], v[22:25]
	v_mfma_f32_16x16x32_bf16 v[14:17], v[142:145], v[208:211], v[14:17]
	s_setprio 0
	s_barrier
	s_add_u32 s0, s34, 0x40000
	s_addc_u32 s1, s35, 0
	s_mov_b32 m0, s79
	v_lshl_add_u64 v[130:131], s[0:1], 0, v[162:163]
	global_load_lds_dwordx4 v[130:131], off
	v_lshl_add_u64 v[130:131], s[0:1], 0, v[164:165]
	s_mov_b32 m0, s92
	s_nop 0
	global_load_lds_dwordx4 v[130:131], off
	s_waitcnt vmcnt(6)
	s_setprio 1
	s_barrier
	v_mfma_f32_16x16x32_bf16 v[46:49], v[212:215], v[146:149], v[46:49]
	v_mfma_f32_16x16x32_bf16 v[42:45], v[220:223], v[146:149], v[42:45]
	v_mfma_f32_16x16x32_bf16 v[30:33], v[212:215], v[154:157], v[30:33]
	v_mfma_f32_16x16x32_bf16 v[26:29], v[220:223], v[154:157], v[26:29]
	v_mfma_f32_16x16x32_bf16 v[18:21], v[212:215], v[178:181], v[18:21]
	v_mfma_f32_16x16x32_bf16 v[10:13], v[220:223], v[178:181], v[10:13]
	v_mfma_f32_16x16x32_bf16 v[6:9], v[212:215], v[204:207], v[6:9]
	v_mfma_f32_16x16x32_bf16 v[2:5], v[220:223], v[204:207], v[2:5]
	v_mfma_f32_16x16x32_bf16 v[46:49], v[216:219], v[150:153], v[46:49]
	v_mfma_f32_16x16x32_bf16 v[42:45], v[242:245], v[150:153], v[42:45]
	v_mfma_f32_16x16x32_bf16 v[30:33], v[216:219], v[158:161], v[30:33]
	v_mfma_f32_16x16x32_bf16 v[26:29], v[242:245], v[158:161], v[26:29]
	v_mfma_f32_16x16x32_bf16 v[18:21], v[216:219], v[182:185], v[18:21]
	v_mfma_f32_16x16x32_bf16 v[10:13], v[242:245], v[182:185], v[10:13]
	v_mfma_f32_16x16x32_bf16 v[6:9], v[216:219], v[208:211], v[6:9]
	v_mfma_f32_16x16x32_bf16 v[2:5], v[242:245], v[208:211], v[2:5]
	s_setprio 0
	v_add_u32_e32 v0, s80, v187
	s_barrier
	ds_read_b128 v[130:133], v0
	ds_read_b128 v[134:137], v0 offset:1024
	ds_read_b128 v[138:141], v0 offset:2048
	ds_read_b128 v[142:145], v0 offset:3072
	s_add_u32 s0, s42, 0x40000
	s_addc_u32 s1, s43, 0
	s_mov_b32 m0, s93
	v_lshl_add_u64 v[212:213], s[0:1], 0, v[162:163]
	ds_read_b128 v[146:149], v202 offset:32768
	ds_read_b128 v[150:153], v202 offset:33792
	ds_read_b128 v[154:157], v202 offset:34816
	ds_read_b128 v[158:161], v202 offset:35840
	ds_read_b128 v[178:181], v202 offset:36864
	ds_read_b128 v[182:185], v202 offset:37888
	ds_read_b128 v[204:207], v202 offset:38912
	ds_read_b128 v[208:211], v202 offset:39936
	global_load_lds_dwordx4 v[212:213], off
	v_lshl_add_u64 v[212:213], s[0:1], 0, v[164:165]
	s_mov_b32 m0, s60
	s_nop 0
	global_load_lds_dwordx4 v[212:213], off
	s_waitcnt lgkmcnt(8)
	s_setprio 1
	s_barrier
	s_waitcnt lgkmcnt(0)
	v_mfma_f32_16x16x32_bf16 v[126:129], v[130:133], v[146:149], v[126:129]
	v_mfma_f32_16x16x32_bf16 v[122:125], v[138:141], v[146:149], v[122:125]
	v_mfma_f32_16x16x32_bf16 v[118:121], v[130:133], v[154:157], v[118:121]
	v_mfma_f32_16x16x32_bf16 v[114:117], v[138:141], v[154:157], v[114:117]
	v_mfma_f32_16x16x32_bf16 v[102:105], v[130:133], v[178:181], v[102:105]
	v_mfma_f32_16x16x32_bf16 v[98:101], v[138:141], v[178:181], v[98:101]
	v_mfma_f32_16x16x32_bf16 v[86:89], v[130:133], v[204:207], v[86:89]
	v_mfma_f32_16x16x32_bf16 v[82:85], v[138:141], v[204:207], v[82:85]
	v_mfma_f32_16x16x32_bf16 v[126:129], v[134:137], v[150:153], v[126:129]
	v_mfma_f32_16x16x32_bf16 v[122:125], v[142:145], v[150:153], v[122:125]
	v_mfma_f32_16x16x32_bf16 v[118:121], v[134:137], v[158:161], v[118:121]
	v_mfma_f32_16x16x32_bf16 v[114:117], v[142:145], v[158:161], v[114:117]
	v_mfma_f32_16x16x32_bf16 v[102:105], v[134:137], v[182:185], v[102:105]
	v_mfma_f32_16x16x32_bf16 v[98:101], v[142:145], v[182:185], v[98:101]
	v_mfma_f32_16x16x32_bf16 v[86:89], v[134:137], v[208:211], v[86:89]
	v_mfma_f32_16x16x32_bf16 v[82:85], v[142:145], v[208:211], v[82:85]
	s_setprio 0
	s_barrier
	s_mov_b32 m0, s81
	v_add_u32_e32 v0, s14, v187
	v_lshl_add_u64 v[194:195], v[194:195], 0, s[88:89]
	ds_read_b128 v[212:215], v0
	ds_read_b128 v[216:219], v0 offset:1024
	ds_read_b128 v[220:223], v0 offset:2048
	ds_read_b128 v[242:245], v0 offset:3072
	global_load_lds_dwordx4 v[194:195], off
	v_lshl_add_u64 v[194:195], v[196:197], 0, s[88:89]
	s_mov_b32 m0, s68
	s_nop 0
	global_load_lds_dwordx4 v[194:195], off
	s_setprio 1
	s_barrier
	s_waitcnt lgkmcnt(0)
	v_mfma_f32_16x16x32_bf16 v[110:113], v[212:215], v[146:149], v[110:113]
	v_mfma_f32_16x16x32_bf16 v[106:109], v[220:223], v[146:149], v[106:109]
	v_mfma_f32_16x16x32_bf16 v[94:97], v[212:215], v[154:157], v[94:97]
	v_mfma_f32_16x16x32_bf16 v[90:93], v[220:223], v[154:157], v[90:93]
	v_mfma_f32_16x16x32_bf16 v[78:81], v[212:215], v[178:181], v[78:81]
	v_mfma_f32_16x16x32_bf16 v[74:77], v[220:223], v[178:181], v[74:77]
	v_mfma_f32_16x16x32_bf16 v[70:73], v[212:215], v[204:207], v[70:73]
	v_mfma_f32_16x16x32_bf16 v[66:69], v[220:223], v[204:207], v[66:69]
	v_mfma_f32_16x16x32_bf16 v[110:113], v[216:219], v[150:153], v[110:113]
	v_mfma_f32_16x16x32_bf16 v[106:109], v[242:245], v[150:153], v[106:109]
	v_mfma_f32_16x16x32_bf16 v[94:97], v[216:219], v[158:161], v[94:97]
	v_mfma_f32_16x16x32_bf16 v[90:93], v[242:245], v[158:161], v[90:93]
	v_mfma_f32_16x16x32_bf16 v[78:81], v[216:219], v[182:185], v[78:81]
	v_mfma_f32_16x16x32_bf16 v[74:77], v[242:245], v[182:185], v[74:77]
	v_mfma_f32_16x16x32_bf16 v[70:73], v[216:219], v[208:211], v[70:73]
	v_mfma_f32_16x16x32_bf16 v[66:69], v[242:245], v[208:211], v[66:69]
	s_setprio 0
	s_mov_b32 m0, s69
	v_lshl_add_u64 v[194:195], v[246:247], 0, s[88:89]
	s_barrier
	ds_read_b128 v[146:149], v202 offset:49152
	ds_read_b128 v[150:153], v202 offset:50176
	ds_read_b128 v[154:157], v202 offset:51200
	ds_read_b128 v[158:161], v202 offset:52224
	ds_read_b128 v[178:181], v202 offset:53248
	ds_read_b128 v[182:185], v202 offset:54272
	ds_read_b128 v[204:207], v202 offset:55296
	ds_read_b128 v[208:211], v202 offset:56320
	global_load_lds_dwordx4 v[194:195], off
	v_lshl_add_u64 v[194:195], v[248:249], 0, s[88:89]
	s_mov_b32 m0, s19
	s_nop 0
	global_load_lds_dwordx4 v[194:195], off
	s_setprio 1
	s_barrier
	s_waitcnt lgkmcnt(0)
	v_mfma_f32_16x16x32_bf16 v[62:65], v[130:133], v[146:149], v[62:65]
	v_mfma_f32_16x16x32_bf16 v[58:61], v[138:141], v[146:149], v[58:61]
	v_mfma_f32_16x16x32_bf16 v[54:57], v[130:133], v[154:157], v[54:57]
	v_mfma_f32_16x16x32_bf16 v[50:53], v[138:141], v[154:157], v[50:53]
	v_mfma_f32_16x16x32_bf16 v[38:41], v[130:133], v[178:181], v[38:41]
	v_mfma_f32_16x16x32_bf16 v[34:37], v[138:141], v[178:181], v[34:37]
	v_mfma_f32_16x16x32_bf16 v[22:25], v[130:133], v[204:207], v[22:25]
	v_mfma_f32_16x16x32_bf16 v[14:17], v[138:141], v[204:207], v[14:17]
	v_mfma_f32_16x16x32_bf16 v[62:65], v[134:137], v[150:153], v[62:65]
	v_mfma_f32_16x16x32_bf16 v[58:61], v[142:145], v[150:153], v[58:61]
	v_mfma_f32_16x16x32_bf16 v[54:57], v[134:137], v[158:161], v[54:57]
	v_mfma_f32_16x16x32_bf16 v[50:53], v[142:145], v[158:161], v[50:53]
	v_mfma_f32_16x16x32_bf16 v[38:41], v[134:137], v[182:185], v[38:41]
	v_mfma_f32_16x16x32_bf16 v[34:37], v[142:145], v[182:185], v[34:37]
	v_mfma_f32_16x16x32_bf16 v[22:25], v[134:137], v[208:211], v[22:25]
	v_mfma_f32_16x16x32_bf16 v[14:17], v[142:145], v[208:211], v[14:17]
	s_setprio 0
	s_barrier
	s_add_u32 s0, s34, 0x40080
	s_addc_u32 s1, s35, 0
	s_mov_b32 m0, s15
	v_lshl_add_u64 v[130:131], s[0:1], 0, v[162:163]
	global_load_lds_dwordx4 v[130:131], off
	v_lshl_add_u64 v[130:131], s[0:1], 0, v[164:165]
	s_mov_b32 m0, s16
	s_nop 0
	global_load_lds_dwordx4 v[130:131], off
	s_waitcnt vmcnt(6)
	s_setprio 1
	s_barrier
	v_mfma_f32_16x16x32_bf16 v[46:49], v[212:215], v[146:149], v[46:49]
	v_mfma_f32_16x16x32_bf16 v[42:45], v[220:223], v[146:149], v[42:45]
	v_mfma_f32_16x16x32_bf16 v[30:33], v[212:215], v[154:157], v[30:33]
	v_mfma_f32_16x16x32_bf16 v[26:29], v[220:223], v[154:157], v[26:29]
	v_mfma_f32_16x16x32_bf16 v[18:21], v[212:215], v[178:181], v[18:21]
	v_mfma_f32_16x16x32_bf16 v[10:13], v[220:223], v[178:181], v[10:13]
	v_mfma_f32_16x16x32_bf16 v[6:9], v[212:215], v[204:207], v[6:9]
	v_mfma_f32_16x16x32_bf16 v[2:5], v[220:223], v[204:207], v[2:5]
	v_mfma_f32_16x16x32_bf16 v[46:49], v[216:219], v[150:153], v[46:49]
	v_mfma_f32_16x16x32_bf16 v[42:45], v[242:245], v[150:153], v[42:45]
	v_mfma_f32_16x16x32_bf16 v[30:33], v[216:219], v[158:161], v[30:33]
	v_mfma_f32_16x16x32_bf16 v[26:29], v[242:245], v[158:161], v[26:29]
	v_mfma_f32_16x16x32_bf16 v[18:21], v[216:219], v[182:185], v[18:21]
	v_mfma_f32_16x16x32_bf16 v[10:13], v[242:245], v[182:185], v[10:13]
	v_mfma_f32_16x16x32_bf16 v[6:9], v[216:219], v[208:211], v[6:9]
	v_mfma_f32_16x16x32_bf16 v[2:5], v[242:245], v[208:211], v[2:5]
	s_setprio 0
	s_add_i32 s26, s26, 2
	s_add_u32 s20, s20, 0x100
	s_addc_u32 s21, s21, 0
	s_add_u32 s24, s24, 0x100
	s_addc_u32 s25, s25, 0
	s_cmp_gt_u32 s26, 13
	s_barrier
	s_cbranch_scc0 .LBB0_1353
	v_readfirstlane_b32 s98, v191
	s_cmpk_gt_u32 s98, 0xff
	s_cbranch_scc1 .Lrl_e0_1353
	s_barrier
